# phase-0 hyena filter items: the 28 block barriers per item that only guard wave-private LDS buffers removed
# baseline (speedup 1.0000x reference)
.LBB0_48:
	v_add_u32_e32 v20, s25, v32
	v_cvt_f32_i32_e32 v66, v20
	s_and_saveexec_b64 s[10:11], s[92:93]
	s_xor_b64 s[28:29], exec, s[10:11]
	s_cbranch_execz .LBB0_64
	v_mul_f32_e32 v20, 0x40c90fdb, v66
	v_div_scale_f32 v66, s[10:11], v65, v65, v20
	v_rcp_f32_e32 v67, v66
	v_div_scale_f32 v68, vcc, v20, v65, v20
	v_fma_f32 v69, -v66, v67, 1.0
	v_fmac_f32_e32 v67, v69, v67
	v_mul_f32_e32 v69, v68, v67
	v_fma_f32 v70, -v66, v69, v68
	v_fmac_f32_e32 v69, v70, v67
	v_fma_f32 v66, -v66, v69, v68
	v_div_fmas_f32 v66, v66, v67, v69
	v_div_fixup_f32 v66, v66, v65, v20
	s_and_saveexec_b64 s[10:11], s[94:95]
	s_xor_b64 s[30:31], exec, s[10:11]
	s_cbranch_execz .LBB0_57
	v_mov_b32_e32 v20, 0
	s_and_saveexec_b64 s[34:35], s[8:9]
	s_cbranch_execz .LBB0_56
	v_mul_f32_e32 v66, v152, v66
	v_and_b32_e32 v67, 0x7fffffff, v66
	v_cmp_nlt_f32_e64 s[10:11], |v66|, s44
	s_and_saveexec_b64 s[12:13], s[10:11]
	s_xor_b64 s[38:39], exec, s[12:13]
	s_cbranch_execz .LBB0_53
	v_lshrrev_b32_e32 v20, 23, v67
	v_add_u32_e32 v20, 0xffffff88, v20
	v_cmp_lt_u32_e32 vcc, 63, v20
	s_nop 1
	v_cndmask_b32_e32 v68, 0, v181, vcc
	v_add_u32_e32 v20, v68, v20
	v_cmp_lt_u32_e64 s[10:11], 31, v20
	s_nop 1
	v_cndmask_b32_e64 v68, 0, v182, s[10:11]
	v_add_u32_e32 v20, v68, v20
	v_cmp_lt_u32_e64 s[12:13], 31, v20
	s_nop 1
	v_cndmask_b32_e64 v68, 0, v182, s[12:13]
	v_add_u32_e32 v82, v68, v20
	v_and_b32_e32 v20, 0x7fffff, v67
	v_or_b32_e32 v80, 0x800000, v20
	v_mad_u64_u32 v[68:69], s[14:15], v80, s45, 0
	v_mov_b32_e32 v20, v69
	v_mad_u64_u32 v[70:71], s[14:15], v80, s46, v[20:21]
	v_mov_b32_e32 v20, v71
	v_mad_u64_u32 v[72:73], s[14:15], v80, s47, v[20:21]
	v_mov_b32_e32 v20, v73
	v_mad_u64_u32 v[74:75], s[14:15], v80, s60, v[20:21]
	v_mov_b32_e32 v20, v75
	v_mad_u64_u32 v[76:77], s[14:15], v80, s61, v[20:21]
	v_mov_b32_e32 v20, v77
	v_mad_u64_u32 v[78:79], s[14:15], v80, s62, v[20:21]
	v_mov_b32_e32 v20, v79
	v_mad_u64_u32 v[80:81], s[14:15], v80, s63, v[20:21]
	v_cndmask_b32_e32 v69, v78, v74, vcc
	v_cndmask_b32_e32 v20, v80, v76, vcc
	v_cndmask_b32_e32 v73, v81, v78, vcc
	v_cndmask_b32_e64 v71, v20, v69, s[10:11]
	v_cndmask_b32_e64 v20, v73, v20, s[10:11]
	v_cndmask_b32_e32 v73, v76, v72, vcc
	v_cndmask_b32_e64 v69, v69, v73, s[10:11]
	v_cndmask_b32_e32 v70, v74, v70, vcc
	v_cndmask_b32_e64 v20, v20, v71, s[12:13]
	v_cndmask_b32_e64 v71, v71, v69, s[12:13]
	v_sub_u32_e32 v75, 32, v82
	v_cndmask_b32_e64 v73, v73, v70, s[10:11]
	v_alignbit_b32 v76, v20, v71, v75
	v_cmp_eq_u32_e64 s[14:15], 0, v82
	v_cndmask_b32_e64 v69, v69, v73, s[12:13]
	v_cndmask_b32_e32 v68, v72, v68, vcc
	v_cndmask_b32_e64 v20, v76, v20, s[14:15]
	v_alignbit_b32 v74, v71, v69, v75
	v_cndmask_b32_e64 v68, v70, v68, s[10:11]
	v_cndmask_b32_e64 v71, v74, v71, s[14:15]
	v_bfe_u32 v77, v20, 29, 1
	v_cndmask_b32_e64 v68, v73, v68, s[12:13]
	v_alignbit_b32 v74, v20, v71, 30
	v_sub_u32_e32 v78, 0, v77
	v_alignbit_b32 v70, v69, v68, v75
	v_xor_b32_e32 v74, v74, v78
	v_cndmask_b32_e64 v69, v70, v69, s[14:15]
	v_alignbit_b32 v70, v71, v69, 30
	v_ffbh_u32_e32 v71, v74
	v_min_u32_e32 v71, 32, v71
	v_alignbit_b32 v68, v69, v68, 30
	v_xor_b32_e32 v70, v70, v78
	v_sub_u32_e32 v72, 31, v71
	v_xor_b32_e32 v68, v68, v78
	v_alignbit_b32 v73, v74, v70, v72
	v_alignbit_b32 v68, v70, v68, v72
	v_alignbit_b32 v69, v73, v68, 9
	v_ffbh_u32_e32 v70, v69
	v_min_u32_e32 v70, 32, v70
	v_lshrrev_b32_e32 v76, 29, v20
	v_not_b32_e32 v72, v70
	v_alignbit_b32 v68, v69, v68, v72
	v_lshlrev_b32_e32 v69, 31, v76
	v_or_b32_e32 v72, 0x33000000, v69
	v_add_lshl_u32 v70, v70, v71, 23
	v_lshrrev_b32_e32 v68, 9, v68
	v_sub_u32_e32 v70, v72, v70
	v_or_b32_e32 v69, 0.5, v69
	v_lshlrev_b32_e32 v71, 23, v71
	v_or_b32_e32 v68, v70, v68
	v_lshrrev_b32_e32 v70, 9, v73
	v_sub_u32_e32 v69, v69, v71
	v_or_b32_e32 v69, v70, v69
	v_mul_f32_e32 v70, 0x3fc90fda, v69
	v_fma_f32 v71, v69, s64, -v70
	v_fmac_f32_e32 v71, 0x33a22168, v69
	v_fmac_f32_e32 v71, 0x3fc90fda, v68
	v_lshrrev_b32_e32 v20, 30, v20
	v_add_f32_e32 v68, v70, v71
	v_add_u32_e32 v20, v77, v20

.LBB0_66:
	s_or_b64 exec, exec, s[10:11]
	ds_write_b32 v149, v20
	s_waitcnt lgkmcnt(0)
	global_load_dword v20, v[2:3], off
	global_load_dword v89, v[4:5], off
	global_load_dword v90, v[36:37], off
	global_load_dword v91, v[38:39], off
	global_load_dword v92, v[40:41], off
	global_load_dword v93, v[42:43], off
	global_load_dword v94, v[44:45], off
	global_load_dword v95, v[46:47], off
	global_load_dword v96, v[48:49], off
	global_load_dword v97, v[50:51], off
	global_load_dword v98, v[52:53], off
	global_load_dword v99, v[54:55], off
	global_load_dword v110, v[4:5], off offset:256
	global_load_dword v111, v[4:5], off offset:512
	global_load_dword v112, v[4:5], off offset:768
	global_load_dword v113, v[4:5], off offset:1024
	global_load_dword v114, v[4:5], off offset:1280
	global_load_dword v115, v[4:5], off offset:1536
	global_load_dword v116, v[4:5], off offset:1792
	global_load_dword v117, v[4:5], off offset:2048
	global_load_dword v118, v[4:5], off offset:2304
	global_load_dword v119, v[4:5], off offset:2560
	global_load_dword v120, v[4:5], off offset:2816
	global_load_dword v121, v[4:5], off offset:3072
	global_load_dword v122, v[4:5], off offset:3328
	global_load_dword v123, v[4:5], off offset:3584
	global_load_dword v124, v[4:5], off offset:3840
	global_load_dword v125, v[6:7], off
	global_load_dword v126, v[8:9], off
	global_load_dword v127, v[10:11], off
	global_load_dword v128, v[12:13], off
	global_load_dword v129, v[14:15], off
	global_load_dword v130, v[16:17], off
	global_load_dword v131, v[34:35], off
	ds_read_b128 v[66:69], v1
	ds_read_b128 v[70:73], v1 offset:16
	ds_read_b128 v[74:77], v1 offset:32
	ds_read_b128 v[78:81], v1 offset:48
	ds_read_b128 v[82:85], v1 offset:64
	ds_read_b96 v[86:88], v1 offset:80
	ds_read2_b32 v[100:101], v1 offset0:23 offset1:24
	ds_read2_b32 v[102:103], v1 offset0:25 offset1:26
	ds_read2_b32 v[104:105], v1 offset0:27 offset1:28
	ds_read2_b32 v[106:107], v1 offset0:29 offset1:30
	ds_read2_b32 v[108:109], v1 offset0:31 offset1:32
	s_waitcnt vmcnt(32) lgkmcnt(10)
	v_fmac_f32_e32 v20, v66, v89
	s_waitcnt vmcnt(30) lgkmcnt(4)
	v_pk_mul_f32 v[90:91], v[100:101], v[90:91]
	s_waitcnt vmcnt(28) lgkmcnt(3)
	v_pk_mul_f32 v[92:93], v[102:103], v[92:93]
	s_waitcnt vmcnt(26) lgkmcnt(2)
	v_pk_mul_f32 v[94:95], v[104:105], v[94:95]
	s_waitcnt vmcnt(24) lgkmcnt(1)
	v_pk_mul_f32 v[96:97], v[106:107], v[96:97]
	s_waitcnt vmcnt(22) lgkmcnt(0)
	v_pk_mul_f32 v[98:99], v[108:109], v[98:99]
	s_waitcnt vmcnt(21)
	v_fmac_f32_e32 v20, v67, v110
	s_waitcnt vmcnt(20)
	v_fmac_f32_e32 v20, v68, v111
	s_waitcnt vmcnt(19)
	v_fmac_f32_e32 v20, v69, v112
	s_waitcnt vmcnt(18)
	v_fmac_f32_e32 v20, v70, v113
	s_waitcnt vmcnt(17)
	v_fmac_f32_e32 v20, v71, v114
	s_waitcnt vmcnt(16)
	v_fmac_f32_e32 v20, v72, v115
	s_waitcnt vmcnt(15)
	v_fmac_f32_e32 v20, v73, v116
	s_waitcnt vmcnt(14)
	v_fmac_f32_e32 v20, v74, v117
	s_waitcnt vmcnt(13)
	v_fmac_f32_e32 v20, v75, v118
	s_waitcnt vmcnt(12)
	v_fmac_f32_e32 v20, v76, v119
	s_waitcnt vmcnt(11)
	v_fmac_f32_e32 v20, v77, v120
	s_waitcnt vmcnt(10)
	v_fmac_f32_e32 v20, v78, v121
	s_waitcnt vmcnt(9)
	v_fmac_f32_e32 v20, v79, v122
	s_waitcnt vmcnt(8)
	v_fmac_f32_e32 v20, v80, v123
	s_waitcnt vmcnt(7)
	v_fmac_f32_e32 v20, v81, v124
	s_waitcnt vmcnt(6)
	v_fmac_f32_e32 v20, v82, v125
	s_waitcnt vmcnt(5)
	v_fmac_f32_e32 v20, v83, v126
	s_waitcnt vmcnt(4)
	v_fmac_f32_e32 v20, v84, v127
	s_waitcnt vmcnt(3)
	v_fmac_f32_e32 v20, v85, v128
	s_waitcnt vmcnt(2)
	v_fmac_f32_e32 v20, v86, v129
	s_waitcnt vmcnt(1)
	v_fmac_f32_e32 v20, v87, v130
	s_waitcnt vmcnt(0)
	v_fmac_f32_e32 v20, v88, v131
	v_add_f32_e32 v20, v20, v90
	v_add_f32_e32 v20, v20, v91
	v_add_f32_e32 v20, v20, v92
	v_add_f32_e32 v20, v20, v93
	v_add_f32_e32 v20, v20, v94
	v_add_f32_e32 v20, v20, v95
	v_add_f32_e32 v20, v20, v96
	v_add_f32_e32 v20, v20, v97
	v_add_f32_e32 v20, v20, v98
	v_add_f32_e32 v20, v20, v99
	v_mul_f32_e32 v66, v64, v20
	v_and_b32_e32 v67, 0x7fffffff, v66
	v_cmp_nlt_f32_e64 s[10:11], |v66|, s44
	s_and_saveexec_b64 s[12:13], s[10:11]
	s_xor_b64 s[28:29], exec, s[12:13]
	s_cbranch_execz .LBB0_68
	v_lshrrev_b32_e32 v20, 23, v67
	v_add_u32_e32 v20, 0xffffff88, v20
	v_cmp_lt_u32_e32 vcc, 63, v20
	s_nop 1
	v_cndmask_b32_e32 v68, 0, v181, vcc
	v_add_u32_e32 v20, v68, v20
	v_cmp_lt_u32_e64 s[10:11], 31, v20
	s_nop 1
	v_cndmask_b32_e64 v68, 0, v182, s[10:11]
	v_add_u32_e32 v20, v68, v20
	v_cmp_lt_u32_e64 s[12:13], 31, v20
	s_nop 1
	v_cndmask_b32_e64 v68, 0, v182, s[12:13]
	v_add_u32_e32 v82, v68, v20
	v_and_b32_e32 v20, 0x7fffff, v67
	v_or_b32_e32 v80, 0x800000, v20
	v_mad_u64_u32 v[68:69], s[14:15], v80, s45, 0
	v_mov_b32_e32 v20, v69
	v_mad_u64_u32 v[70:71], s[14:15], v80, s46, v[20:21]
	v_mov_b32_e32 v20, v71
	v_mad_u64_u32 v[72:73], s[14:15], v80, s47, v[20:21]
	v_mov_b32_e32 v20, v73
	v_mad_u64_u32 v[74:75], s[14:15], v80, s60, v[20:21]
	v_mov_b32_e32 v20, v75
	v_mad_u64_u32 v[76:77], s[14:15], v80, s61, v[20:21]
	v_mov_b32_e32 v20, v77
	v_mad_u64_u32 v[78:79], s[14:15], v80, s62, v[20:21]
	v_mov_b32_e32 v20, v79
	v_mad_u64_u32 v[80:81], s[14:15], v80, s63, v[20:21]
	v_cndmask_b32_e32 v69, v78, v74, vcc
	v_cndmask_b32_e32 v20, v80, v76, vcc
	v_cndmask_b32_e32 v73, v81, v78, vcc
	v_cndmask_b32_e64 v71, v20, v69, s[10:11]
	v_cndmask_b32_e64 v20, v73, v20, s[10:11]
	v_cndmask_b32_e32 v73, v76, v72, vcc
	v_cndmask_b32_e64 v69, v69, v73, s[10:11]
	v_cndmask_b32_e32 v70, v74, v70, vcc
	v_cndmask_b32_e64 v20, v20, v71, s[12:13]
	v_cndmask_b32_e64 v71, v71, v69, s[12:13]
	v_sub_u32_e32 v75, 32, v82
	v_cndmask_b32_e64 v73, v73, v70, s[10:11]
	v_alignbit_b32 v76, v20, v71, v75
	v_cmp_eq_u32_e64 s[14:15], 0, v82
	v_cndmask_b32_e64 v69, v69, v73, s[12:13]
	v_cndmask_b32_e32 v68, v72, v68, vcc
	v_cndmask_b32_e64 v20, v76, v20, s[14:15]
	v_alignbit_b32 v74, v71, v69, v75
	v_cndmask_b32_e64 v68, v70, v68, s[10:11]
	v_cndmask_b32_e64 v71, v74, v71, s[14:15]
	v_bfe_u32 v77, v20, 29, 1
	v_cndmask_b32_e64 v68, v73, v68, s[12:13]
	v_alignbit_b32 v74, v20, v71, 30
	v_sub_u32_e32 v78, 0, v77
	v_alignbit_b32 v70, v69, v68, v75
	v_xor_b32_e32 v74, v74, v78
	v_cndmask_b32_e64 v69, v70, v69, s[14:15]
	v_alignbit_b32 v70, v71, v69, 30
	v_ffbh_u32_e32 v71, v74
	v_min_u32_e32 v71, 32, v71
	v_alignbit_b32 v68, v69, v68, 30
	v_xor_b32_e32 v70, v70, v78
	v_sub_u32_e32 v72, 31, v71
	v_xor_b32_e32 v68, v68, v78
	v_alignbit_b32 v73, v74, v70, v72
	v_alignbit_b32 v68, v70, v68, v72
	v_alignbit_b32 v69, v73, v68, 9
	v_ffbh_u32_e32 v70, v69
	v_min_u32_e32 v70, 32, v70
	v_lshrrev_b32_e32 v76, 29, v20
	v_not_b32_e32 v72, v70
	v_alignbit_b32 v68, v69, v68, v72
	v_lshlrev_b32_e32 v69, 31, v76
	v_or_b32_e32 v72, 0x33000000, v69
	v_add_lshl_u32 v70, v70, v71, 23
	v_lshrrev_b32_e32 v68, 9, v68
	v_sub_u32_e32 v70, v72, v70
	v_or_b32_e32 v69, 0.5, v69
	v_lshlrev_b32_e32 v71, 23, v71
	v_or_b32_e32 v68, v70, v68
	v_lshrrev_b32_e32 v70, 9, v73
	v_sub_u32_e32 v69, v69, v71
	v_or_b32_e32 v69, v70, v69
	v_mul_f32_e32 v70, 0x3fc90fda, v69
	v_fma_f32 v71, v69, s64, -v70
	v_fmac_f32_e32 v71, 0x33a22168, v69
	v_fmac_f32_e32 v71, 0x3fc90fda, v68
	v_lshrrev_b32_e32 v20, 30, v20
	v_add_f32_e32 v68, v70, v71
	v_add_u32_e32 v20, v77, v20
.LBB0_68:
	s_andn2_saveexec_b64 s[10:11], s[28:29]
	v_mul_f32_e64 v20, |v66|, s65
	v_rndne_f32_e32 v69, v20
	v_cvt_i32_f32_e32 v20, v69
	v_fma_f32 v68, v69, s66, |v66|
	v_fmac_f32_e32 v68, 0xb3a22168, v69
	v_fmac_f32_e32 v68, 0xa7c234c4, v69
	s_or_b64 exec, exec, s[10:11]
	v_mul_f32_e32 v69, v68, v68
	v_fmamk_f32 v70, v69, 0xb94c1982, v179
	v_fmaak_f32 v70, v69, v70, 0xbe2aaa9d
	v_mul_f32_e32 v70, v69, v70
	v_fmac_f32_e32 v68, v68, v70
	v_fmamk_f32 v70, v69, 0x37d75334, v180
	v_fmaak_f32 v70, v69, v70, 0x3d2aabf7
	v_fmaak_f32 v70, v69, v70, 0xbf000004
	v_fma_f32 v69, v69, v70, 1.0
	v_and_b32_e32 v70, 1, v20
	v_lshlrev_b32_e32 v20, 30, v20
	v_cmp_eq_u32_e32 vcc, 0, v70
	v_and_b32_e32 v20, 0x80000000, v20
	v_xor_b32_e32 v67, v67, v66
	v_cndmask_b32_e32 v68, v69, v68, vcc
	v_xor_b32_e32 v20, v67, v20
	v_xor_b32_e32 v20, v20, v68
	v_cmp_class_f32_e64 vcc, v66, s67
	s_nop 0
	v_cndmask_b32_e32 v20, v184, v20, vcc
	ds_write_b32 v149, v20
	s_waitcnt lgkmcnt(0)
	global_load_dword v20, v[56:57], off
	s_mov_b64 s[10:11], 0
	v_mov_b32_e32 v66, v1

.LBB0_74:
	s_andn2_saveexec_b64 s[10:11], s[28:29]
	v_mul_f32_e64 v20, |v66|, s65
	v_rndne_f32_e32 v69, v20
	v_cvt_i32_f32_e32 v20, v69
	v_fma_f32 v68, v69, s66, |v66|
	v_fmac_f32_e32 v68, 0xb3a22168, v69
	v_fmac_f32_e32 v68, 0xa7c234c4, v69
	s_or_b64 exec, exec, s[10:11]
	v_mul_f32_e32 v69, v68, v68
	v_fmamk_f32 v70, v69, 0xb94c1982, v179
	v_fmaak_f32 v70, v69, v70, 0xbe2aaa9d
	v_mul_f32_e32 v70, v69, v70
	v_fmac_f32_e32 v68, v68, v70
	v_fmamk_f32 v70, v69, 0x37d75334, v180
	v_fmaak_f32 v70, v69, v70, 0x3d2aabf7
	v_fmaak_f32 v70, v69, v70, 0xbf000004
	v_fma_f32 v69, v69, v70, 1.0
	v_and_b32_e32 v70, 1, v20
	v_lshlrev_b32_e32 v20, 30, v20
	v_cmp_eq_u32_e32 vcc, 0, v70
	v_and_b32_e32 v20, 0x80000000, v20
	v_xor_b32_e32 v67, v67, v66
	v_cndmask_b32_e32 v68, v69, v68, vcc
	v_xor_b32_e32 v20, v67, v20
	v_xor_b32_e32 v20, v20, v68
	v_cmp_class_f32_e64 vcc, v66, s67
	s_nop 0
	v_cndmask_b32_e32 v20, v184, v20, vcc
	ds_write_b32 v149, v20
	s_waitcnt lgkmcnt(0)
	global_load_dword v20, v[58:59], off
	s_mov_b64 s[10:11], 0
	v_mov_b32_e32 v66, v1

.LBB0_82:
	s_ashr_i32 s7, s6, 31
	s_lshl_b64 s[10:11], s[6:7], 18
	v_mov_b32_e32 v34, 0
	v_lshl_add_u64 v[98:99], v[30:31], 0, s[10:11]
	s_mov_b64 s[10:11], 0
	v_mov_b32_e32 v20, v177
	v_mov_b32_e32 v35, v34
	v_mov_b32_e32 v40, v34
	v_mov_b32_e32 v41, v34
	v_mov_b32_e32 v44, v34
	v_mov_b32_e32 v45, v34
	v_mov_b32_e32 v48, v34
	v_mov_b32_e32 v49, v34
	v_mov_b32_e32 v50, v34
	v_mov_b32_e32 v51, v34
	v_mov_b32_e32 v54, v34
	v_mov_b32_e32 v55, v34
	v_mov_b32_e32 v58, v34
	v_mov_b32_e32 v59, v34
	v_mov_b32_e32 v62, v34
	v_mov_b32_e32 v63, v34
	v_mov_b32_e32 v68, v34
	v_mov_b32_e32 v69, v34
	v_mov_b32_e32 v72, v34
	v_mov_b32_e32 v73, v34
	v_mov_b32_e32 v76, v34
	v_mov_b32_e32 v77, v34
	v_mov_b32_e32 v80, v34
	v_mov_b32_e32 v81, v34
	v_mov_b32_e32 v82, v34
	v_mov_b32_e32 v83, v34
	v_mov_b32_e32 v86, v34
	v_mov_b32_e32 v87, v34
	v_mov_b32_e32 v90, v34
	v_mov_b32_e32 v91, v34
	v_mov_b32_e32 v96, v34
	v_mov_b32_e32 v97, v34
	v_mov_b32_e32 v36, v34
	v_mov_b32_e32 v37, v34
	v_mov_b32_e32 v42, v34
	v_mov_b32_e32 v43, v34
	v_mov_b32_e32 v66, v34
	v_mov_b32_e32 v67, v34
	v_mov_b32_e32 v74, v34
	v_mov_b32_e32 v75, v34
	v_mov_b32_e32 v52, v34
	v_mov_b32_e32 v53, v34
	v_mov_b32_e32 v60, v34
	v_mov_b32_e32 v61, v34
	v_mov_b32_e32 v84, v34
	v_mov_b32_e32 v85, v34
	v_mov_b32_e32 v92, v34
	v_mov_b32_e32 v93, v34
	v_mov_b32_e32 v38, v34
	v_mov_b32_e32 v39, v34
	v_mov_b32_e32 v46, v34
	v_mov_b32_e32 v47, v34
	v_mov_b32_e32 v56, v34
	v_mov_b32_e32 v57, v34
	v_mov_b32_e32 v64, v34
	v_mov_b32_e32 v65, v34
	v_mov_b32_e32 v70, v34
	v_mov_b32_e32 v71, v34
	v_mov_b32_e32 v78, v34
	v_mov_b32_e32 v79, v34
	v_mov_b32_e32 v88, v34
	v_mov_b32_e32 v89, v34
	v_mov_b32_e32 v94, v34
	v_mov_b32_e32 v95, v34
	s_waitcnt lgkmcnt(0)
.LBB0_83:
	v_lshl_add_u64 v[100:101], v[98:99], 0, s[10:11]
	s_movk_i32 s12, 0x1000
	v_add_co_u32_e32 v102, vcc, s12, v100
	ds_read_b128 v[2:5], v20
	ds_read_b128 v[10:13], v20 offset:256
	ds_read_b128 v[6:9], v20 offset:512
	ds_read_b128 v[14:17], v20 offset:768
	s_movk_i32 s13, 0x2000
	global_load_dword v121, v[100:101], off
	global_load_dword v120, v[100:101], off offset:256
	global_load_dword v123, v[100:101], off offset:512
	global_load_dword v122, v[100:101], off offset:768
	global_load_dword v125, v[100:101], off offset:1024
	global_load_dword v124, v[100:101], off offset:1280
	global_load_dword v131, v[100:101], off offset:1536
	global_load_dword v130, v[100:101], off offset:1792
	global_load_dword v133, v[100:101], off offset:2048
	global_load_dword v132, v[100:101], off offset:2304
	global_load_dword v135, v[100:101], off offset:2560
	global_load_dword v134, v[100:101], off offset:2816
	global_load_dword v137, v[100:101], off offset:3072
	global_load_dword v136, v[100:101], off offset:3328
	global_load_dword v139, v[100:101], off offset:3584
	global_load_dword v138, v[100:101], off offset:3840
	v_addc_co_u32_e32 v103, vcc, 0, v101, vcc
	v_add_co_u32_e32 v104, vcc, s13, v100
	s_movk_i32 s14, 0x3000
	s_nop 0
	v_addc_co_u32_e32 v105, vcc, 0, v101, vcc
	v_add_co_u32_e32 v188, vcc, s14, v100
	s_waitcnt lgkmcnt(0)
	v_mov_b32_e32 v206, v14
	v_addc_co_u32_e32 v189, vcc, 0, v101, vcc
	global_load_dword v117, v[104:105], off offset:-4096
	global_load_dword v116, v[102:103], off offset:256
	global_load_dword v119, v[102:103], off offset:512
	global_load_dword v118, v[102:103], off offset:768
	global_load_dword v191, v[102:103], off offset:1024
	global_load_dword v190, v[102:103], off offset:1280
	global_load_dword v193, v[102:103], off offset:1536
	global_load_dword v192, v[102:103], off offset:1792
	global_load_dword v127, v[102:103], off offset:2048
	global_load_dword v126, v[102:103], off offset:2304
	global_load_dword v129, v[102:103], off offset:2560
	global_load_dword v128, v[102:103], off offset:2816
	global_load_dword v195, v[102:103], off offset:3072
	global_load_dword v194, v[102:103], off offset:3328
	global_load_dword v197, v[102:103], off offset:3584
	global_load_dword v196, v[102:103], off offset:3840
	global_load_dword v101, v[104:105], off
	global_load_dword v100, v[104:105], off offset:256
	s_nop 0
	global_load_dword v103, v[104:105], off offset:512
	global_load_dword v102, v[104:105], off offset:768
	global_load_dword v199, v[104:105], off offset:1024
	global_load_dword v198, v[104:105], off offset:1280
	global_load_dword v201, v[104:105], off offset:1536
	global_load_dword v200, v[104:105], off offset:1792
	global_load_dword v109, v[104:105], off offset:2048
	global_load_dword v108, v[104:105], off offset:2304
	global_load_dword v111, v[104:105], off offset:2560
	global_load_dword v110, v[104:105], off offset:2816
	global_load_dword v203, v[104:105], off offset:3072
	global_load_dword v202, v[104:105], off offset:3328
	global_load_dword v205, v[104:105], off offset:3584
	global_load_dword v204, v[104:105], off offset:3840
	s_nop 0
	global_load_dword v105, v[188:189], off
	global_load_dword v104, v[188:189], off offset:256
	global_load_dword v107, v[188:189], off offset:512
	global_load_dword v106, v[188:189], off offset:768
	global_load_dword v141, v[188:189], off offset:1024
	global_load_dword v140, v[188:189], off offset:1280
	global_load_dword v143, v[188:189], off offset:1536
	global_load_dword v142, v[188:189], off offset:1792
	global_load_dword v113, v[188:189], off offset:2048
	global_load_dword v112, v[188:189], off offset:2304
	global_load_dword v115, v[188:189], off offset:2560
	global_load_dword v114, v[188:189], off offset:2816
	global_load_dword v145, v[188:189], off offset:3072
	global_load_dword v144, v[188:189], off offset:3328
	global_load_dword v147, v[188:189], off offset:3584
	global_load_dword v146, v[188:189], off offset:3840
	v_mov_b32_e32 v207, v6
	v_mov_b32_e32 v188, v10
	v_mov_b32_e32 v189, v6
	v_mov_b32_e32 v6, v11
	v_mov_b32_e32 v208, v12
	v_mov_b32_e32 v209, v8
	s_add_u32 s10, s10, 0x4000
	v_mov_b32_e32 v212, v16
	v_mov_b32_e32 v213, v8
	v_mov_b32_e32 v210, v5
	v_mov_b32_e32 v214, v13
	v_mov_b32_e32 v8, v13
	s_addc_u32 s11, s11, 0
	v_mov_b32_e32 v216, v17
	v_add_u32_e32 v20, 16, v20
	s_cmp_eq_u32 s10, 0x40000
	s_waitcnt vmcnt(62)
	v_mov_b32_e32 v226, v121
	v_pk_fma_f32 v[94:95], v[120:121], v[2:3], v[94:95] op_sel_hi:[1,0,1]
	v_pk_fma_f32 v[92:93], v[120:121], v[10:11], v[92:93] op_sel_hi:[1,0,1]
	s_waitcnt vmcnt(60)
	v_pk_fma_f32 v[88:89], v[122:123], v[2:3], v[88:89] op_sel_hi:[1,0,1]
	v_pk_fma_f32 v[84:85], v[122:123], v[10:11], v[84:85] op_sel_hi:[1,0,1]
	s_waitcnt vmcnt(58)
	v_pk_fma_f32 v[78:79], v[124:125], v[2:3], v[78:79] op_sel_hi:[1,0,1]
	v_mov_b32_e32 v218, v125
	s_waitcnt vmcnt(56)
	v_pk_fma_f32 v[70:71], v[130:131], v[2:3], v[70:71] op_sel_hi:[1,0,1]
	v_mov_b32_e32 v220, v131
	s_waitcnt vmcnt(54)
	v_pk_fma_f32 v[64:65], v[132:133], v[2:3], v[64:65] op_sel_hi:[1,0,1]
	v_pk_fma_f32 v[60:61], v[132:133], v[10:11], v[60:61] op_sel_hi:[1,0,1]
	s_waitcnt vmcnt(52)
	v_pk_fma_f32 v[56:57], v[134:135], v[2:3], v[56:57] op_sel_hi:[1,0,1]
	v_pk_fma_f32 v[52:53], v[134:135], v[10:11], v[52:53] op_sel_hi:[1,0,1]
	s_waitcnt vmcnt(50)
	v_pk_fma_f32 v[46:47], v[136:137], v[2:3], v[46:47] op_sel_hi:[1,0,1]
	v_mov_b32_e32 v222, v137
	s_waitcnt vmcnt(48)
	v_pk_fma_f32 v[38:39], v[138:139], v[2:3], v[38:39] op_sel_hi:[1,0,1]
	v_mov_b32_e32 v224, v139
	v_pk_fma_f32 v[90:91], v[120:121], v[206:207], v[90:91] op_sel_hi:[0,1,1]
	v_mov_b32_e32 v120, v123
	v_pk_fma_f32 v[82:83], v[122:123], v[206:207], v[82:83] op_sel_hi:[0,1,1]
	v_mov_b32_e32 v122, v133
	v_pk_fma_f32 v[76:77], v[124:125], v[188:189], v[76:77] op_sel_hi:[0,1,1]
	v_pk_fma_f32 v[68:69], v[130:131], v[188:189], v[68:69] op_sel_hi:[0,1,1]
	v_pk_fma_f32 v[44:45], v[136:137], v[188:189], v[44:45] op_sel_hi:[0,1,1]
	v_pk_fma_f32 v[34:35], v[138:139], v[188:189], v[34:35] op_sel_hi:[0,1,1]
	v_pk_fma_f32 v[74:75], v[124:125], v[14:15], v[74:75] op_sel_hi:[1,0,1]
	v_pk_fma_f32 v[66:67], v[130:131], v[14:15], v[66:67] op_sel_hi:[1,0,1]
	v_mov_b32_e32 v124, v135
	v_pk_fma_f32 v[42:43], v[136:137], v[14:15], v[42:43] op_sel_hi:[1,0,1]
	v_pk_fma_f32 v[36:37], v[138:139], v[14:15], v[36:37] op_sel_hi:[1,0,1]
	v_pk_fma_f32 v[80:81], v[218:219], v[188:189], v[80:81] op_sel_hi:[0,1,1]
	v_pk_fma_f32 v[72:73], v[220:221], v[188:189], v[72:73] op_sel_hi:[0,1,1]
	v_pk_fma_f32 v[48:49], v[222:223], v[188:189], v[48:49] op_sel_hi:[0,1,1]
	v_pk_fma_f32 v[40:41], v[224:225], v[188:189], v[40:41] op_sel_hi:[0,1,1]
	v_pk_fma_f32 v[86:87], v[120:121], v[206:207], v[86:87] op_sel_hi:[0,1,1]
	v_pk_fma_f32 v[62:63], v[122:123], v[206:207], v[62:63] op_sel_hi:[0,1,1]
	s_waitcnt vmcnt(46)
	v_pk_fma_f32 v[94:95], v[116:117], v[2:3], v[94:95] op_sel:[0,1,0]
	s_waitcnt vmcnt(44)
	v_pk_fma_f32 v[88:89], v[118:119], v[2:3], v[88:89] op_sel:[0,1,0]
	s_waitcnt vmcnt(42)
	v_pk_fma_f32 v[78:79], v[190:191], v[2:3], v[78:79] op_sel:[0,1,0]
	s_waitcnt vmcnt(40)
	v_pk_fma_f32 v[70:71], v[192:193], v[2:3], v[70:71] op_sel:[0,1,0]
	s_waitcnt vmcnt(38)
	v_pk_fma_f32 v[64:65], v[126:127], v[2:3], v[64:65] op_sel:[0,1,0]
	s_waitcnt vmcnt(36)
	v_pk_fma_f32 v[56:57], v[128:129], v[2:3], v[56:57] op_sel:[0,1,0]
	s_waitcnt vmcnt(34)
	v_pk_fma_f32 v[46:47], v[194:195], v[2:3], v[46:47] op_sel:[0,1,0]
	s_waitcnt vmcnt(32)
	v_pk_fma_f32 v[2:3], v[196:197], v[2:3], v[38:39] op_sel:[0,1,0]
	v_pk_fma_f32 v[38:39], v[116:117], v[10:11], v[92:93] op_sel:[0,1,0]
	v_pk_fma_f32 v[84:85], v[118:119], v[10:11], v[84:85] op_sel:[0,1,0]
	v_pk_fma_f32 v[60:61], v[126:127], v[10:11], v[60:61] op_sel:[0,1,0]
	v_pk_fma_f32 v[10:11], v[128:129], v[10:11], v[52:53] op_sel:[0,1,0]
	v_mov_b32_e32 v52, v191
	v_mov_b32_e32 v92, v193
	v_mov_b32_e32 v120, v195
	v_mov_b32_e32 v122, v197
	v_pk_fma_f32 v[58:59], v[132:133], v[206:207], v[58:59] op_sel_hi:[0,1,1]
	v_pk_fma_f32 v[50:51], v[134:135], v[206:207], v[50:51] op_sel_hi:[0,1,1]
	v_pk_fma_f32 v[96:97], v[226:227], v[206:207], v[96:97] op_sel_hi:[0,1,1]
	v_pk_fma_f32 v[54:55], v[124:125], v[206:207], v[54:55] op_sel_hi:[0,1,1]
	v_pk_fma_f32 v[76:77], v[190:191], v[6:7], v[76:77] op_sel_hi:[0,1,1]
	v_pk_fma_f32 v[68:69], v[192:193], v[6:7], v[68:69] op_sel_hi:[0,1,1]
	v_pk_fma_f32 v[44:45], v[194:195], v[6:7], v[44:45] op_sel_hi:[0,1,1]
	v_pk_fma_f32 v[34:35], v[196:197], v[6:7], v[34:35] op_sel_hi:[0,1,1]
	v_mov_b32_e32 v124, v117
	v_mov_b32_e32 v130, v119
	v_pk_fma_f32 v[74:75], v[190:191], v[14:15], v[74:75] op_sel:[0,1,0]
	v_pk_fma_f32 v[66:67], v[192:193], v[14:15], v[66:67] op_sel:[0,1,0]
	v_mov_b32_e32 v132, v127
	v_mov_b32_e32 v134, v129
	v_pk_fma_f32 v[42:43], v[194:195], v[14:15], v[42:43] op_sel:[0,1,0]
	v_pk_fma_f32 v[36:37], v[196:197], v[14:15], v[36:37] op_sel:[0,1,0]
	s_waitcnt vmcnt(27)
	v_mov_b32_e32 v14, v199
	s_waitcnt vmcnt(25)
	v_mov_b32_e32 v136, v201
	s_waitcnt vmcnt(19)
	v_mov_b32_e32 v138, v203
	s_waitcnt vmcnt(17)
	v_mov_b32_e32 v188, v205
	v_pk_fma_f32 v[52:53], v[52:53], v[6:7], v[80:81] op_sel_hi:[0,1,1]
	v_pk_fma_f32 v[72:73], v[92:93], v[6:7], v[72:73] op_sel_hi:[0,1,1]
	v_pk_fma_f32 v[48:49], v[120:121], v[6:7], v[48:49] op_sel_hi:[0,1,1]
	v_pk_fma_f32 v[40:41], v[122:123], v[6:7], v[40:41] op_sel_hi:[0,1,1]
	v_mov_b32_e32 v6, v15
	v_mov_b32_e32 v190, v101
	v_mov_b32_e32 v192, v103
	v_mov_b32_e32 v194, v109
	v_mov_b32_e32 v196, v111
	s_waitcnt vmcnt(11)
	v_mov_b32_e32 v206, v141
	s_waitcnt vmcnt(9)
	v_mov_b32_e32 v218, v143
	s_waitcnt vmcnt(3)
	v_mov_b32_e32 v220, v145
	s_waitcnt vmcnt(1)
	v_mov_b32_e32 v222, v147
	v_pk_fma_f32 v[80:81], v[100:101], v[4:5], v[94:95] op_sel_hi:[1,0,1]
	v_pk_fma_f32 v[88:89], v[102:103], v[4:5], v[88:89] op_sel_hi:[1,0,1]
	v_pk_fma_f32 v[78:79], v[198:199], v[4:5], v[78:79] op_sel_hi:[1,0,1]
	v_pk_fma_f32 v[70:71], v[200:201], v[4:5], v[70:71] op_sel_hi:[1,0,1]
	v_pk_fma_f32 v[64:65], v[108:109], v[4:5], v[64:65] op_sel_hi:[1,0,1]
	v_pk_fma_f32 v[56:57], v[110:111], v[4:5], v[56:57] op_sel_hi:[1,0,1]
	v_pk_fma_f32 v[46:47], v[202:203], v[4:5], v[46:47] op_sel_hi:[1,0,1]
	v_pk_fma_f32 v[2:3], v[204:205], v[4:5], v[2:3] op_sel_hi:[1,0,1]
	v_pk_fma_f32 v[4:5], v[100:101], v[12:13], v[38:39] op_sel_hi:[1,0,1]
	v_pk_fma_f32 v[84:85], v[102:103], v[12:13], v[84:85] op_sel_hi:[1,0,1]
	v_pk_fma_f32 v[60:61], v[108:109], v[12:13], v[60:61] op_sel_hi:[1,0,1]
	v_pk_fma_f32 v[10:11], v[110:111], v[12:13], v[10:11] op_sel_hi:[1,0,1]
	v_pk_fma_f32 v[12:13], v[198:199], v[208:209], v[76:77] op_sel_hi:[0,1,1]
	v_pk_fma_f32 v[68:69], v[200:201], v[208:209], v[68:69] op_sel_hi:[0,1,1]
	v_pk_fma_f32 v[44:45], v[202:203], v[208:209], v[44:45] op_sel_hi:[0,1,1]
	v_pk_fma_f32 v[34:35], v[204:205], v[208:209], v[34:35] op_sel_hi:[0,1,1]
	v_pk_fma_f32 v[96:97], v[124:125], v[6:7], v[96:97] op_sel_hi:[0,1,1]
	v_pk_fma_f32 v[90:91], v[116:117], v[6:7], v[90:91] op_sel_hi:[0,1,1]
	v_pk_fma_f32 v[86:87], v[130:131], v[6:7], v[86:87] op_sel_hi:[0,1,1]
	v_pk_fma_f32 v[82:83], v[118:119], v[6:7], v[82:83] op_sel_hi:[0,1,1]
	v_pk_fma_f32 v[62:63], v[132:133], v[6:7], v[62:63] op_sel_hi:[0,1,1]
	v_pk_fma_f32 v[58:59], v[126:127], v[6:7], v[58:59] op_sel_hi:[0,1,1]
	v_pk_fma_f32 v[54:55], v[134:135], v[6:7], v[54:55] op_sel_hi:[0,1,1]
	v_pk_fma_f32 v[6:7], v[128:129], v[6:7], v[50:51] op_sel_hi:[0,1,1]
	v_pk_fma_f32 v[14:15], v[14:15], v[208:209], v[52:53] op_sel_hi:[0,1,1]
	v_pk_fma_f32 v[50:51], v[136:137], v[208:209], v[72:73] op_sel_hi:[0,1,1]
	v_pk_fma_f32 v[48:49], v[138:139], v[208:209], v[48:49] op_sel_hi:[0,1,1]
	v_pk_fma_f32 v[40:41], v[188:189], v[208:209], v[40:41] op_sel_hi:[0,1,1]
	v_mov_b32_e32 v224, v105
	v_mov_b32_e32 v226, v107
	v_mov_b32_e32 v228, v113
	v_mov_b32_e32 v230, v115
	v_pk_fma_f32 v[74:75], v[198:199], v[16:17], v[74:75] op_sel_hi:[1,0,1]
	v_pk_fma_f32 v[66:67], v[200:201], v[16:17], v[66:67] op_sel_hi:[1,0,1]
	v_pk_fma_f32 v[42:43], v[202:203], v[16:17], v[42:43] op_sel_hi:[1,0,1]
	v_pk_fma_f32 v[36:37], v[204:205], v[16:17], v[36:37] op_sel_hi:[1,0,1]
	v_pk_fma_f32 v[94:95], v[104:105], v[210:211], v[80:81] op_sel_hi:[1,0,1]
	s_waitcnt vmcnt(0)
	v_pk_fma_f32 v[38:39], v[146:147], v[210:211], v[2:3] op_sel_hi:[1,0,1]
	v_pk_fma_f32 v[92:93], v[104:105], v[214:215], v[4:5] op_sel_hi:[1,0,1]
	v_pk_fma_f32 v[52:53], v[114:115], v[214:215], v[10:11] op_sel_hi:[1,0,1]
	v_pk_fma_f32 v[76:77], v[140:141], v[8:9], v[12:13] op_sel_hi:[0,1,1]
	v_pk_fma_f32 v[68:69], v[142:143], v[8:9], v[68:69] op_sel_hi:[0,1,1]
	v_pk_fma_f32 v[44:45], v[144:145], v[8:9], v[44:45] op_sel_hi:[0,1,1]
	v_pk_fma_f32 v[34:35], v[146:147], v[8:9], v[34:35] op_sel_hi:[0,1,1]
	v_pk_fma_f32 v[2:3], v[190:191], v[212:213], v[96:97] op_sel_hi:[0,1,1]
	v_pk_fma_f32 v[4:5], v[100:101], v[212:213], v[90:91] op_sel_hi:[0,1,1]
	v_pk_fma_f32 v[10:11], v[192:193], v[212:213], v[86:87] op_sel_hi:[0,1,1]
	v_pk_fma_f32 v[12:13], v[102:103], v[212:213], v[82:83] op_sel_hi:[0,1,1]
	v_pk_fma_f32 v[62:63], v[194:195], v[212:213], v[62:63] op_sel_hi:[0,1,1]
	v_pk_fma_f32 v[58:59], v[108:109], v[212:213], v[58:59] op_sel_hi:[0,1,1]
	v_pk_fma_f32 v[54:55], v[196:197], v[212:213], v[54:55] op_sel_hi:[0,1,1]
	v_pk_fma_f32 v[6:7], v[110:111], v[212:213], v[6:7] op_sel_hi:[0,1,1]
	v_pk_fma_f32 v[80:81], v[206:207], v[8:9], v[14:15] op_sel_hi:[0,1,1]
	v_pk_fma_f32 v[72:73], v[218:219], v[8:9], v[50:51] op_sel_hi:[0,1,1]
	v_pk_fma_f32 v[48:49], v[220:221], v[8:9], v[48:49] op_sel_hi:[0,1,1]
	v_pk_fma_f32 v[40:41], v[222:223], v[8:9], v[40:41] op_sel_hi:[0,1,1]
	v_mov_b32_e32 v8, v17
	v_pk_fma_f32 v[88:89], v[106:107], v[210:211], v[88:89] op_sel_hi:[1,0,1]
	v_pk_fma_f32 v[78:79], v[140:141], v[210:211], v[78:79] op_sel_hi:[1,0,1]
	v_pk_fma_f32 v[70:71], v[142:143], v[210:211], v[70:71] op_sel_hi:[1,0,1]
	v_pk_fma_f32 v[64:65], v[112:113], v[210:211], v[64:65] op_sel_hi:[1,0,1]
	v_pk_fma_f32 v[56:57], v[114:115], v[210:211], v[56:57] op_sel_hi:[1,0,1]
	v_pk_fma_f32 v[46:47], v[144:145], v[210:211], v[46:47] op_sel_hi:[1,0,1]
	v_pk_fma_f32 v[84:85], v[106:107], v[214:215], v[84:85] op_sel_hi:[1,0,1]
	v_pk_fma_f32 v[60:61], v[112:113], v[214:215], v[60:61] op_sel_hi:[1,0,1]
	v_pk_fma_f32 v[74:75], v[140:141], v[216:217], v[74:75] op_sel_hi:[1,0,1]
	v_pk_fma_f32 v[66:67], v[142:143], v[216:217], v[66:67] op_sel_hi:[1,0,1]
	v_pk_fma_f32 v[42:43], v[144:145], v[216:217], v[42:43] op_sel_hi:[1,0,1]
	v_pk_fma_f32 v[36:37], v[146:147], v[216:217], v[36:37] op_sel_hi:[1,0,1]
	v_pk_fma_f32 v[96:97], v[224:225], v[8:9], v[2:3] op_sel_hi:[0,1,1]
	v_pk_fma_f32 v[90:91], v[104:105], v[8:9], v[4:5] op_sel_hi:[0,1,1]
	v_pk_fma_f32 v[86:87], v[226:227], v[8:9], v[10:11] op_sel_hi:[0,1,1]
	v_pk_fma_f32 v[82:83], v[106:107], v[8:9], v[12:13] op_sel_hi:[0,1,1]
	v_pk_fma_f32 v[62:63], v[228:229], v[8:9], v[62:63] op_sel_hi:[0,1,1]
	v_pk_fma_f32 v[58:59], v[112:113], v[8:9], v[58:59] op_sel_hi:[0,1,1]
	v_pk_fma_f32 v[54:55], v[230:231], v[8:9], v[54:55] op_sel_hi:[0,1,1]
	v_pk_fma_f32 v[50:51], v[114:115], v[8:9], v[6:7] op_sel_hi:[0,1,1]
	s_cbranch_scc0 .LBB0_83
	s_lshl_b64 s[10:11], s[6:7], 19
	v_cvt_f32_i32_e32 v2, v32
	s_add_u32 s12, s42, s10
	s_addc_u32 s13, s43, s11
	s_lshl_b64 s[10:11], s[6:7], 22
	s_add_u32 s14, s3, s10
	s_addc_u32 s15, s97, s11
	v_div_scale_f32 v3, s[10:11], v33, v33, -v2
	v_rcp_f32_e32 v4, v3
	s_and_b64 s[10:11], s[18:19], exec
	s_cselect_b32 s12, s12, s14
	s_cselect_b32 s14, 9, 12
	v_fma_f32 v5, -v3, v4, 1.0
	v_fmac_f32_e32 v4, v5, v4
	v_div_scale_f32 v5, vcc, -v2, v33, -v2
	v_mul_f32_e32 v6, v5, v4
	v_fma_f32 v7, -v3, v6, v5
	v_fmac_f32_e32 v6, v7, v4
	v_fma_f32 v3, -v3, v6, v5
	v_div_fmas_f32 v3, v3, v4, v6
	v_div_fixup_f32 v16, v3, v33, -v2
	v_mul_f32_e64 v2, |v161|, v16
	v_mul_f32_e32 v3, 0x3fb8aa3b, v2
	v_fma_f32 v4, v2, s68, -v3
	v_rndne_f32_e32 v5, v3
	v_fmac_f32_e32 v4, 0x32a5705f, v2
	v_sub_f32_e32 v3, v3, v5
	v_add_f32_e32 v3, v3, v4
	v_exp_f32_e32 v3, v3
	v_cvt_i32_f32_e32 v4, v5
	v_cmp_ngt_f32_e32 vcc, s69, v2
	v_lshlrev_b32_e32 v5, s14, v148
	v_lshlrev_b32_e32 v20, 1, v5
	v_ldexp_f32 v3, v3, v4
	v_cndmask_b32_e32 v3, 0, v3, vcc
	v_cmp_nlt_f32_e32 vcc, s70, v2
	s_cselect_b32 s13, s13, s15
	v_lshl_add_u64 v[8:9], s[12:13], 0, v[20:21]
	v_cndmask_b32_e32 v2, v185, v3, vcc
	v_or_b32_e32 v3, 1, v32
	v_cvt_f32_i32_e32 v3, v3
	v_add_f32_e32 v2, 0x3d4ccccd, v2
	v_mul_f32_e32 v6, v2, v95
	v_bfe_u32 v7, v6, 16, 1
	v_div_scale_f32 v4, s[10:11], v33, v33, -v3
	v_rcp_f32_e32 v5, v4
	v_add3_u32 v11, v6, v7, s71
	v_sub_u32_e32 v2, s74, v32
	v_fma_f32 v7, -v4, v5, 1.0
	v_fmac_f32_e32 v5, v7, v5
	v_div_scale_f32 v7, vcc, -v3, v33, -v3
	v_mul_f32_e32 v10, v7, v5
	v_fma_f32 v12, -v4, v10, v7
	v_fmac_f32_e32 v10, v12, v5
	v_fma_f32 v4, -v4, v10, v7
	v_div_fmas_f32 v4, v4, v5, v10
	v_div_fixup_f32 v17, v4, v33, -v3
	v_mul_f32_e64 v7, |v161|, v17
	v_mul_f32_e32 v3, 0x3fb8aa3b, v7
	v_fma_f32 v4, v7, s68, -v3
	v_rndne_f32_e32 v5, v3
	v_fmac_f32_e32 v4, 0x32a5705f, v7
	v_sub_f32_e32 v3, v3, v5
	v_add_f32_e32 v3, v3, v4
	v_exp_f32_e32 v10, v3
	v_cvt_i32_f32_e32 v12, v5
	v_cmp_ngt_f32_e32 vcc, s69, v7
	v_ashrrev_i32_e32 v3, 31, v2
	v_lshlrev_b64 v[2:3], 1, v[2:3]
	v_ldexp_f32 v10, v10, v12
	v_or_b32_e32 v12, 2, v32
	v_cvt_f32_i32_e32 v12, v12
	v_cndmask_b32_e32 v10, 0, v10, vcc
	v_cmp_nlt_f32_e32 vcc, s70, v7
	v_lshl_add_u64 v[4:5], v[8:9], 0, v[2:3]
	s_nop 0
	v_cndmask_b32_e32 v7, v185, v10, vcc
	v_div_scale_f32 v10, s[10:11], v33, v33, -v12
	v_rcp_f32_e32 v13, v10
	v_add_f32_e32 v7, 0x3d4ccccd, v7
	v_mul_f32_e32 v7, v7, v93
	v_bfe_u32 v14, v7, 16, 1
	v_fma_f32 v15, -v10, v13, 1.0
	v_fmac_f32_e32 v13, v15, v13
	v_div_scale_f32 v15, vcc, -v12, v33, -v12
	v_mul_f32_e32 v20, v15, v13
	v_fma_f32 v93, -v10, v20, v15
	v_fmac_f32_e32 v20, v93, v13
	v_fma_f32 v10, -v10, v20, v15
	v_div_fmas_f32 v10, v10, v13, v20
	v_div_fixup_f32 v93, v10, v33, -v12
	v_mul_f32_e64 v10, |v161|, v93
	v_mul_f32_e32 v12, 0x3fb8aa3b, v10
	v_fma_f32 v13, v10, s68, -v12
	v_rndne_f32_e32 v15, v12
	v_fmac_f32_e32 v13, 0x32a5705f, v10
	v_sub_f32_e32 v12, v12, v15
	v_add_f32_e32 v12, v12, v13
	v_or_b32_e32 v13, 3, v32
	v_cvt_f32_i32_e32 v13, v13
	v_exp_f32_e32 v12, v12
	v_cvt_i32_f32_e32 v15, v15
	v_add3_u32 v14, v7, v14, s71
	v_div_scale_f32 v20, s[10:11], v33, v33, -v13
	v_rcp_f32_e32 v95, v20
	v_add_f32_e64 v98, |v6|, |v7|
	v_ldexp_f32 v6, v12, v15
	v_perm_b32 v11, v11, v14, s72
	v_fma_f32 v7, -v20, v95, 1.0
	v_fmac_f32_e32 v95, v7, v95
	v_div_scale_f32 v7, vcc, -v13, v33, -v13
	v_mul_f32_e32 v12, v7, v95
	v_fma_f32 v15, -v20, v12, v7
	v_fmac_f32_e32 v12, v15, v95
	v_fma_f32 v7, -v20, v12, v7
	v_div_fmas_f32 v7, v7, v95, v12
	v_div_fixup_f32 v95, v7, v33, -v13
	v_mul_f32_e64 v12, |v161|, v95
	v_mul_f32_e32 v7, 0x3fb8aa3b, v12
	v_fma_f32 v13, v12, s68, -v7
	v_rndne_f32_e32 v15, v7
	v_fmac_f32_e32 v13, 0x32a5705f, v12
	v_sub_f32_e32 v7, v7, v15
	v_add_f32_e32 v7, v7, v13
	v_exp_f32_e32 v13, v7
	v_cvt_i32_f32_e32 v15, v15
	v_cmp_ngt_f32_e32 vcc, s69, v10
	s_nop 1
	v_cndmask_b32_e32 v6, 0, v6, vcc
	v_cmp_nlt_f32_e32 vcc, s70, v10
	s_nop 1
	v_cndmask_b32_e32 v7, v185, v6, vcc
	v_ldexp_f32 v6, v13, v15
	v_cmp_ngt_f32_e32 vcc, s69, v12
	s_nop 1
	v_cndmask_b32_e32 v6, 0, v6, vcc
	v_cmp_nlt_f32_e32 vcc, s70, v12
	s_nop 1
	v_cndmask_b32_e32 v6, v185, v6, vcc
	v_pk_add_f32 v[6:7], v[6:7], s[96:97] op_sel_hi:[1,0]
	s_nop 0
	v_pk_mul_f32 v[6:7], v[6:7], v[96:97]
	s_nop 0
	v_and_b32_sdwa v10, v7, v186 dst_sel:DWORD dst_unused:UNUSED_PAD src0_sel:WORD_1 src1_sel:DWORD
	v_and_b32_sdwa v13, v6, v186 dst_sel:DWORD dst_unused:UNUSED_PAD src0_sel:WORD_1 src1_sel:DWORD
	v_add_f32_e64 v12, v98, |v7|
	v_add3_u32 v13, v6, v13, s71
	v_add3_u32 v7, v7, v10, s71
	v_perm_b32 v10, v7, v13, s72
	global_store_dwordx2 v[4:5], v[10:11], off offset:-6
	v_mul_f32_e64 v4, |v163|, v16
	v_mul_f32_e32 v5, 0x3fb8aa3b, v4
	v_add_f32_e64 v14, v12, |v6|
	v_fma_f32 v6, v4, s68, -v5
	v_rndne_f32_e32 v7, v5
	v_fmac_f32_e32 v6, 0x32a5705f, v4
	v_sub_f32_e32 v5, v5, v7
	v_add_f32_e32 v5, v5, v6
	v_exp_f32_e32 v5, v5
	v_cvt_i32_f32_e32 v6, v7
	v_cmp_ngt_f32_e32 vcc, s69, v4
	v_lshlrev_b32_e32 v7, s14, v153
	v_lshlrev_b32_e32 v20, 1, v7
	v_ldexp_f32 v5, v5, v6
	v_cndmask_b32_e32 v5, 0, v5, vcc
	v_cmp_nlt_f32_e32 vcc, s70, v4
	v_mul_f32_e64 v7, |v163|, v17
	v_lshl_add_u64 v[10:11], s[12:13], 0, v[20:21]
	v_cndmask_b32_e32 v4, v185, v5, vcc
	v_add_f32_e32 v4, 0x3d4ccccd, v4
	v_mul_f32_e32 v6, v4, v94
	v_mul_f32_e32 v4, 0x3fb8aa3b, v7
	v_fma_f32 v5, v7, s68, -v4
	v_rndne_f32_e32 v12, v4
	v_fmac_f32_e32 v5, 0x32a5705f, v7
	v_sub_f32_e32 v4, v4, v12
	v_add_f32_e32 v4, v4, v5
	v_exp_f32_e32 v13, v4
	v_cvt_i32_f32_e32 v12, v12
	v_cmp_ngt_f32_e32 vcc, s69, v7
	v_bfe_u32 v4, v6, 16, 1
	v_add3_u32 v15, v6, v4, s71
	v_ldexp_f32 v12, v13, v12
	v_cndmask_b32_e32 v12, 0, v12, vcc
	v_cmp_nlt_f32_e32 vcc, s70, v7
	v_lshl_add_u64 v[4:5], v[10:11], 0, v[2:3]
	s_nop 0
	v_cndmask_b32_e32 v7, v185, v12, vcc
	v_mul_f32_e64 v12, |v163|, v93
	v_mul_f32_e32 v13, 0x3fb8aa3b, v12
	v_fma_f32 v20, v12, s68, -v13
	v_rndne_f32_e32 v33, v13
	v_fmac_f32_e32 v20, 0x32a5705f, v12
	v_sub_f32_e32 v13, v13, v33
	v_add_f32_e32 v13, v13, v20
	v_exp_f32_e32 v13, v13
	v_cvt_i32_f32_e32 v20, v33
	v_add_f32_e32 v7, 0x3d4ccccd, v7
	v_mul_f32_e32 v7, v7, v92
	v_bfe_u32 v33, v7, 16, 1
	v_add_f32_e64 v92, |v6|, |v7|
	v_ldexp_f32 v6, v13, v20
	v_mul_f32_e64 v13, |v163|, v95
	v_add3_u32 v33, v7, v33, s71
	v_mul_f32_e32 v7, 0x3fb8aa3b, v13
	v_fma_f32 v20, v13, s68, -v7
	v_rndne_f32_e32 v94, v7
	v_fmac_f32_e32 v20, 0x32a5705f, v13
	v_sub_f32_e32 v7, v7, v94
	v_add_f32_e32 v7, v7, v20
	v_exp_f32_e32 v20, v7
	v_cvt_i32_f32_e32 v94, v94
	v_cmp_ngt_f32_e32 vcc, s69, v12
	s_nop 1
	v_cndmask_b32_e32 v6, 0, v6, vcc
	v_cmp_nlt_f32_e32 vcc, s70, v12
	s_nop 1
	v_cndmask_b32_e32 v7, v185, v6, vcc
	v_ldexp_f32 v6, v20, v94
	v_cmp_ngt_f32_e32 vcc, s69, v13
	s_nop 1
	v_cndmask_b32_e32 v6, 0, v6, vcc
	v_cmp_nlt_f32_e32 vcc, s70, v13
	s_nop 1
	v_cndmask_b32_e32 v6, v185, v6, vcc
	v_pk_add_f32 v[6:7], v[6:7], s[96:97] op_sel_hi:[1,0]
	s_nop 0
	v_pk_mul_f32 v[6:7], v[6:7], v[90:91]
	s_nop 0
	v_and_b32_sdwa v12, v7, v186 dst_sel:DWORD dst_unused:UNUSED_PAD src0_sel:WORD_1 src1_sel:DWORD
	v_and_b32_sdwa v13, v6, v186 dst_sel:DWORD dst_unused:UNUSED_PAD src0_sel:WORD_1 src1_sel:DWORD
	v_add_f32_e64 v20, v92, |v7|
	v_add3_u32 v13, v6, v13, s71
	v_add3_u32 v7, v7, v12, s71
	v_perm_b32 v12, v7, v13, s72
	v_perm_b32 v13, v15, v33, s72
	global_store_dwordx2 v[4:5], v[12:13], off offset:-6
	v_add_f32_e64 v4, v20, |v6|
	ds_write2st64_b32 v162, v14, v4 offset0:40 offset1:41
	v_mul_f32_e64 v4, |v164|, v16
	v_mul_f32_e32 v5, 0x3fb8aa3b, v4
	v_fma_f32 v6, v4, s68, -v5
	v_rndne_f32_e32 v7, v5
	v_fmac_f32_e32 v6, 0x32a5705f, v4
	v_sub_f32_e32 v5, v5, v7
	v_add_f32_e32 v5, v5, v6
	v_exp_f32_e32 v5, v5
	v_cvt_i32_f32_e32 v6, v7
	v_cmp_ngt_f32_e32 vcc, s69, v4
	v_lshlrev_b32_e32 v7, s14, v154
	v_lshlrev_b32_e32 v20, 1, v7
	v_ldexp_f32 v5, v5, v6
	v_cndmask_b32_e32 v5, 0, v5, vcc
	v_cmp_nlt_f32_e32 vcc, s70, v4
	v_mul_f32_e64 v7, |v164|, v17
	v_lshl_add_u64 v[12:13], s[12:13], 0, v[20:21]
	v_cndmask_b32_e32 v4, v185, v5, vcc
	v_add_f32_e32 v4, 0x3d4ccccd, v4
	v_mul_f32_e32 v6, v4, v89
	v_mul_f32_e32 v4, 0x3fb8aa3b, v7
	v_fma_f32 v5, v7, s68, -v4
	v_rndne_f32_e32 v14, v4
	v_fmac_f32_e32 v5, 0x32a5705f, v7
	v_sub_f32_e32 v4, v4, v14
	v_add_f32_e32 v4, v4, v5
	v_exp_f32_e32 v15, v4
	v_cvt_i32_f32_e32 v14, v14
	v_cmp_ngt_f32_e32 vcc, s69, v7
	v_bfe_u32 v4, v6, 16, 1
	v_add3_u32 v20, v6, v4, s71
	v_ldexp_f32 v14, v15, v14
	v_cndmask_b32_e32 v14, 0, v14, vcc
	v_cmp_nlt_f32_e32 vcc, s70, v7
	v_lshl_add_u64 v[4:5], v[12:13], 0, v[2:3]
	s_nop 0
	v_cndmask_b32_e32 v7, v185, v14, vcc
	v_mul_f32_e64 v14, |v164|, v93
	v_add_f32_e32 v7, 0x3d4ccccd, v7
	v_mul_f32_e32 v15, 0x3fb8aa3b, v14
	v_mul_f32_e32 v7, v7, v85
	v_fma_f32 v33, v14, s68, -v15
	v_rndne_f32_e32 v85, v15
	v_fmac_f32_e32 v33, 0x32a5705f, v14
	v_sub_f32_e32 v15, v15, v85
	v_add_f32_e32 v15, v15, v33
	v_exp_f32_e32 v15, v15
	v_cvt_i32_f32_e32 v33, v85
	v_bfe_u32 v85, v7, 16, 1
	v_add_f32_e64 v89, |v6|, |v7|
	v_add3_u32 v85, v7, v85, s71
	v_ldexp_f32 v6, v15, v33
	v_mul_f32_e64 v15, |v164|, v95
	v_mul_f32_e32 v7, 0x3fb8aa3b, v15
	v_fma_f32 v33, v15, s68, -v7
	v_rndne_f32_e32 v90, v7
	v_fmac_f32_e32 v33, 0x32a5705f, v15
	v_sub_f32_e32 v7, v7, v90
	v_add_f32_e32 v7, v7, v33
	v_exp_f32_e32 v33, v7
	v_cvt_i32_f32_e32 v90, v90
	v_cmp_ngt_f32_e32 vcc, s69, v14
	s_nop 1
	v_cndmask_b32_e32 v6, 0, v6, vcc
	v_cmp_nlt_f32_e32 vcc, s70, v14
	s_nop 1
	v_cndmask_b32_e32 v7, v185, v6, vcc
	v_ldexp_f32 v6, v33, v90
	v_cmp_ngt_f32_e32 vcc, s69, v15
	s_nop 1
	v_cndmask_b32_e32 v6, 0, v6, vcc
	v_cmp_nlt_f32_e32 vcc, s70, v15
	s_nop 1
	v_cndmask_b32_e32 v6, v185, v6, vcc
	v_pk_add_f32 v[6:7], v[6:7], s[96:97] op_sel_hi:[1,0]
	s_nop 0
	v_pk_mul_f32 v[6:7], v[6:7], v[86:87]
	s_nop 0
	v_and_b32_sdwa v14, v7, v186 dst_sel:DWORD dst_unused:UNUSED_PAD src0_sel:WORD_1 src1_sel:DWORD
	v_and_b32_sdwa v15, v6, v186 dst_sel:DWORD dst_unused:UNUSED_PAD src0_sel:WORD_1 src1_sel:DWORD
	v_add_f32_e64 v33, v89, |v7|
	v_add3_u32 v15, v6, v15, s71
	v_add3_u32 v7, v7, v14, s71
	v_perm_b32 v14, v7, v15, s72
	v_perm_b32 v15, v20, v85, s72
	global_store_dwordx2 v[4:5], v[14:15], off offset:-6
	v_mul_f32_e64 v4, |v165|, v16
	v_mul_f32_e32 v5, 0x3fb8aa3b, v4
	v_add_f32_e64 v33, v33, |v6|
	v_fma_f32 v6, v4, s68, -v5
	v_rndne_f32_e32 v7, v5
	v_fmac_f32_e32 v6, 0x32a5705f, v4
	v_sub_f32_e32 v5, v5, v7
	v_add_f32_e32 v5, v5, v6
	v_exp_f32_e32 v5, v5
	v_cvt_i32_f32_e32 v6, v7
	v_cmp_ngt_f32_e32 vcc, s69, v4
	v_lshlrev_b32_e32 v7, s14, v155
	v_lshlrev_b32_e32 v20, 1, v7
	v_ldexp_f32 v5, v5, v6
	v_cndmask_b32_e32 v5, 0, v5, vcc
	v_cmp_nlt_f32_e32 vcc, s70, v4
	v_mul_f32_e64 v7, |v165|, v17
	v_lshl_add_u64 v[14:15], s[12:13], 0, v[20:21]
	v_cndmask_b32_e32 v4, v185, v5, vcc
	v_add_f32_e32 v4, 0x3d4ccccd, v4
	v_mul_f32_e32 v6, v4, v88
	v_mul_f32_e32 v4, 0x3fb8aa3b, v7
	v_fma_f32 v5, v7, s68, -v4
	v_rndne_f32_e32 v20, v4
	v_fmac_f32_e32 v5, 0x32a5705f, v7
	v_sub_f32_e32 v4, v4, v20
	v_add_f32_e32 v4, v4, v5
	v_exp_f32_e32 v85, v4
	v_cvt_i32_f32_e32 v20, v20
	v_cmp_ngt_f32_e32 vcc, s69, v7
	v_bfe_u32 v4, v6, 16, 1
	v_add3_u32 v86, v6, v4, s71
	v_ldexp_f32 v20, v85, v20
	v_cndmask_b32_e32 v20, 0, v20, vcc
	v_cmp_nlt_f32_e32 vcc, s70, v7
	v_lshl_add_u64 v[4:5], v[14:15], 0, v[2:3]
	s_nop 0
	v_cndmask_b32_e32 v7, v185, v20, vcc
	v_add_f32_e32 v7, 0x3d4ccccd, v7
	v_mul_f32_e64 v20, |v165|, v93
	v_mul_f32_e32 v7, v7, v84
	v_mul_f32_e32 v84, 0x3fb8aa3b, v20
	v_fma_f32 v85, v20, s68, -v84
	v_rndne_f32_e32 v87, v84
	v_fmac_f32_e32 v85, 0x32a5705f, v20
	v_sub_f32_e32 v84, v84, v87
	v_add_f32_e32 v84, v84, v85
	v_exp_f32_e32 v84, v84
	v_cvt_i32_f32_e32 v85, v87
	v_bfe_u32 v87, v7, 16, 1
	v_add_f32_e64 v88, |v6|, |v7|
	v_add3_u32 v87, v7, v87, s71
	v_ldexp_f32 v6, v84, v85
	v_mul_f32_e64 v84, |v165|, v95
	v_mul_f32_e32 v7, 0x3fb8aa3b, v84
	v_fma_f32 v85, v84, s68, -v7
	v_rndne_f32_e32 v89, v7
	v_fmac_f32_e32 v85, 0x32a5705f, v84
	v_sub_f32_e32 v7, v7, v89
	v_add_f32_e32 v7, v7, v85
	v_exp_f32_e32 v85, v7
	v_cvt_i32_f32_e32 v89, v89
	v_cmp_ngt_f32_e32 vcc, s69, v20
	s_nop 1
	v_cndmask_b32_e32 v6, 0, v6, vcc
	v_cmp_nlt_f32_e32 vcc, s70, v20
	s_nop 1
	v_cndmask_b32_e32 v7, v185, v6, vcc
	v_ldexp_f32 v6, v85, v89
	v_cmp_ngt_f32_e32 vcc, s69, v84
	s_nop 1
	v_cndmask_b32_e32 v6, 0, v6, vcc
	v_cmp_nlt_f32_e32 vcc, s70, v84
	s_nop 1
	v_cndmask_b32_e32 v6, v185, v6, vcc
	v_pk_add_f32 v[6:7], v[6:7], s[96:97] op_sel_hi:[1,0]
	s_nop 0
	v_pk_mul_f32 v[6:7], v[6:7], v[82:83]
	s_nop 0
	v_and_b32_sdwa v82, v7, v186 dst_sel:DWORD dst_unused:UNUSED_PAD src0_sel:WORD_1 src1_sel:DWORD
	v_and_b32_sdwa v83, v6, v186 dst_sel:DWORD dst_unused:UNUSED_PAD src0_sel:WORD_1 src1_sel:DWORD
	v_add_f32_e64 v20, v88, |v7|
	v_add3_u32 v83, v6, v83, s71
	v_add3_u32 v7, v7, v82, s71
	v_perm_b32 v82, v7, v83, s72
	v_mul_f32_e64 v7, |v166|, v16
	v_mul_f32_e32 v84, 0x3fb8aa3b, v7
	v_perm_b32 v83, v86, v87, s72
	v_fma_f32 v85, v7, s68, -v84
	v_rndne_f32_e32 v86, v84
	v_fmac_f32_e32 v85, 0x32a5705f, v7
	v_sub_f32_e32 v84, v84, v86
	v_add_f32_e32 v84, v84, v85
	v_exp_f32_e32 v84, v84
	v_cvt_i32_f32_e32 v85, v86
	global_store_dwordx2 v[4:5], v[82:83], off offset:-6
	v_add_f32_e64 v4, v20, |v6|
	ds_write2st64_b32 v162, v33, v4 offset0:42 offset1:43
	v_ldexp_f32 v4, v84, v85
	v_cmp_ngt_f32_e32 vcc, s69, v7
	v_add_u32_e32 v5, s74, v32
	s_nop 0
	v_cndmask_b32_e32 v4, 0, v4, vcc
	v_cmp_nlt_f32_e32 vcc, s70, v7
	s_nop 1
	v_cndmask_b32_e32 v4, v185, v4, vcc
	v_add_f32_e32 v4, 0x3d4ccccd, v4
	v_mul_f32_e32 v4, v4, v79
	v_mul_f32_e64 v79, |v166|, v17
	v_mul_f32_e32 v6, 0x3fb8aa3b, v79
	v_cmp_eq_u32_e32 vcc, 0, v32
	v_fma_f32 v7, v79, s68, -v6
	v_rndne_f32_e32 v82, v6
	v_cndmask_b32_e64 v20, v4, 0, vcc
	v_fmac_f32_e32 v7, 0x32a5705f, v79
	v_sub_f32_e32 v6, v6, v82
	v_bfe_u32 v4, v20, 16, 1
	v_add_f32_e32 v6, v6, v7
	v_add3_u32 v33, v20, v4, s71
	v_cndmask_b32_e64 v4, v5, 0, vcc
	v_exp_f32_e32 v83, v6
	v_cvt_i32_f32_e32 v82, v82
	v_ashrrev_i32_e32 v5, 31, v4
	v_lshlrev_b64 v[4:5], 1, v[4:5]
	v_lshl_add_u64 v[6:7], v[8:9], 0, v[4:5]
	global_store_short_d16_hi v[6:7], v33, off
	v_ldexp_f32 v6, v83, v82
	v_cmp_ngt_f32_e64 s[10:11], s69, v79
	v_ashrrev_i32_e32 v33, 31, v32
	s_nop 0
	v_cndmask_b32_e64 v6, 0, v6, s[10:11]
	v_cmp_nlt_f32_e64 s[10:11], s70, v79
	v_mul_f32_e64 v79, |v166|, v93
	s_nop 0
	v_cndmask_b32_e64 v82, v185, v6, s[10:11]
	v_mul_f32_e32 v6, 0x3fb8aa3b, v79
	v_fma_f32 v7, v79, s68, -v6
	v_rndne_f32_e32 v83, v6
	v_fmac_f32_e32 v7, 0x32a5705f, v79
	v_sub_f32_e32 v6, v6, v83
	v_add_f32_e32 v6, v6, v7
	v_exp_f32_e32 v84, v6
	v_cvt_i32_f32_e32 v83, v83
	v_lshl_add_u64 v[6:7], v[32:33], 0, s[74:75]
	v_cmp_ngt_f32_e64 s[10:11], s69, v79
	v_lshlrev_b64 v[6:7], 1, v[6:7]
	v_ldexp_f32 v32, v84, v83
	v_cndmask_b32_e64 v32, 0, v32, s[10:11]
	v_cmp_nlt_f32_e64 s[10:11], s70, v79
	v_lshl_add_u64 v[8:9], v[8:9], 0, v[6:7]
	s_nop 0
	v_cndmask_b32_e64 v83, v185, v32, s[10:11]
	v_pk_add_f32 v[32:33], v[82:83], s[96:97] op_sel_hi:[1,0]
	s_nop 0
	v_pk_mul_f32 v[32:33], v[32:33], v[80:81]
	v_mul_f32_e64 v81, |v166|, v95
	v_mul_f32_e32 v82, 0x3fb8aa3b, v81
	v_fma_f32 v83, v81, s68, -v82
	v_rndne_f32_e32 v84, v82
	v_fmac_f32_e32 v83, 0x32a5705f, v81
	v_sub_f32_e32 v82, v82, v84
	v_add_f32_e32 v82, v82, v83
	v_exp_f32_e32 v82, v82
	v_cvt_i32_f32_e32 v83, v84
	v_and_b32_sdwa v79, v33, v186 dst_sel:DWORD dst_unused:UNUSED_PAD src0_sel:WORD_1 src1_sel:DWORD
	v_and_b32_sdwa v80, v32, v186 dst_sel:DWORD dst_unused:UNUSED_PAD src0_sel:WORD_1 src1_sel:DWORD
	v_add_f32_e64 v20, |v20|, |v32|
	v_add3_u32 v32, v32, v80, s71
	v_add3_u32 v79, v33, v79, s71
	v_perm_b32 v32, v79, v32, s72
	v_mul_f32_e64 v79, |v167|, v16
	v_add_f32_e64 v20, v20, |v33|
	v_ldexp_f32 v33, v82, v83
	v_cmp_ngt_f32_e64 s[10:11], s69, v81
	v_mul_f32_e32 v80, 0x3fb8aa3b, v79
	v_rndne_f32_e32 v82, v80
	v_cndmask_b32_e64 v33, 0, v33, s[10:11]
	v_cmp_nlt_f32_e64 s[10:11], s70, v81
	v_fma_f32 v81, v79, s68, -v80
	v_fmac_f32_e32 v81, 0x32a5705f, v79
	v_sub_f32_e32 v80, v80, v82
	v_cndmask_b32_e64 v33, v185, v33, s[10:11]
	v_add_f32_e32 v80, v80, v81
	v_add_f32_e32 v33, 0x3d4ccccd, v33
	v_exp_f32_e32 v80, v80
	v_cvt_i32_f32_e32 v81, v82
	v_mul_f32_e32 v33, v33, v75
	v_bfe_u32 v75, v33, 16, 1
	v_add3_u32 v75, v33, v75, s71
	global_store_short_d16_hi v[8:9], v75, off offset:6
	global_store_dword v[8:9], v32, off offset:2
	v_ldexp_f32 v8, v80, v81
	v_cmp_ngt_f32_e64 s[10:11], s69, v79
	v_add_f32_e64 v20, v20, |v33|
	v_mul_f32_e64 v33, |v167|, v17
	v_cndmask_b32_e64 v8, 0, v8, s[10:11]
	v_cmp_nlt_f32_e64 s[10:11], s70, v79
	v_mul_f32_e32 v9, 0x3fb8aa3b, v33
	v_fma_f32 v75, v33, s68, -v9
	v_cndmask_b32_e64 v8, v185, v8, s[10:11]
	v_add_f32_e32 v8, 0x3d4ccccd, v8
	v_mul_f32_e32 v8, v8, v78
	v_rndne_f32_e32 v78, v9
	v_fmac_f32_e32 v75, 0x32a5705f, v33
	v_sub_f32_e32 v9, v9, v78
	v_add_f32_e32 v9, v9, v75
	v_cndmask_b32_e64 v32, v8, 0, vcc
	v_exp_f32_e32 v75, v9
	v_cvt_i32_f32_e32 v78, v78
	v_bfe_u32 v8, v32, 16, 1
	v_add3_u32 v79, v32, v8, s71
	v_lshl_add_u64 v[8:9], v[10:11], 0, v[4:5]
	global_store_short_d16_hi v[8:9], v79, off
	v_mul_f32_e64 v9, |v167|, v93
	v_ldexp_f32 v8, v75, v78
	v_mul_f32_e32 v75, 0x3fb8aa3b, v9
	v_fma_f32 v78, v9, s68, -v75
	v_rndne_f32_e32 v79, v75
	v_fmac_f32_e32 v78, 0x32a5705f, v9
	v_sub_f32_e32 v75, v75, v79
	v_add_f32_e32 v75, v75, v78
	v_exp_f32_e32 v75, v75
	v_cvt_i32_f32_e32 v78, v79
	v_cmp_ngt_f32_e64 s[10:11], s69, v33
	v_lshl_add_u64 v[10:11], v[10:11], 0, v[6:7]
	s_nop 0
	v_cndmask_b32_e64 v8, 0, v8, s[10:11]
	v_cmp_nlt_f32_e64 s[10:11], s70, v33
	v_ldexp_f32 v33, v75, v78
	s_nop 0
	v_cndmask_b32_e64 v8, v185, v8, s[10:11]
	v_cmp_ngt_f32_e64 s[10:11], s69, v9
	s_nop 1
	v_cndmask_b32_e64 v33, 0, v33, s[10:11]
	v_cmp_nlt_f32_e64 s[10:11], s70, v9
	s_nop 1
	v_cndmask_b32_e64 v9, v185, v33, s[10:11]
	v_pk_add_f32 v[8:9], v[8:9], s[96:97] op_sel_hi:[1,0]
	s_nop 0
	v_pk_mul_f32 v[8:9], v[8:9], v[76:77]
	v_mul_f32_e64 v76, |v167|, v95
	v_mul_f32_e32 v77, 0x3fb8aa3b, v76
	v_fma_f32 v78, v76, s68, -v77
	v_rndne_f32_e32 v79, v77
	v_fmac_f32_e32 v78, 0x32a5705f, v76
	v_sub_f32_e32 v77, v77, v79
	v_add_f32_e32 v77, v77, v78
	v_exp_f32_e32 v77, v77
	v_cvt_i32_f32_e32 v78, v79
	v_add_f32_e64 v32, |v32|, |v8|
	v_and_b32_sdwa v33, v9, v186 dst_sel:DWORD dst_unused:UNUSED_PAD src0_sel:WORD_1 src1_sel:DWORD
	v_add3_u32 v33, v9, v33, s71
	v_add_f32_e64 v9, v32, |v9|
	v_ldexp_f32 v32, v77, v78
	v_cmp_ngt_f32_e64 s[10:11], s69, v76
	v_and_b32_sdwa v75, v8, v186 dst_sel:DWORD dst_unused:UNUSED_PAD src0_sel:WORD_1 src1_sel:DWORD
	v_add3_u32 v8, v8, v75, s71
	v_cndmask_b32_e64 v32, 0, v32, s[10:11]
	v_cmp_nlt_f32_e64 s[10:11], s70, v76
	v_perm_b32 v8, v33, v8, s72
	v_mul_f32_e64 v33, |v168|, v16
	v_cndmask_b32_e64 v32, v185, v32, s[10:11]
	v_add_f32_e32 v32, 0x3d4ccccd, v32
	v_mul_f32_e32 v32, v32, v74
	v_bfe_u32 v74, v32, 16, 1
	v_add3_u32 v74, v32, v74, s71
	global_store_short_d16_hi v[10:11], v74, off offset:6
	v_mul_f32_e32 v74, 0x3fb8aa3b, v33
	v_fma_f32 v75, v33, s68, -v74
	v_rndne_f32_e32 v76, v74
	v_fmac_f32_e32 v75, 0x32a5705f, v33
	v_sub_f32_e32 v74, v74, v76
	v_add_f32_e32 v74, v74, v75
	v_exp_f32_e32 v74, v74
	v_cvt_i32_f32_e32 v75, v76
	global_store_dword v[10:11], v8, off offset:2
	v_add_f32_e64 v8, v9, |v32|
	ds_write2st64_b32 v162, v20, v8 offset0:44 offset1:45
	v_ldexp_f32 v8, v74, v75
	v_cmp_ngt_f32_e64 s[10:11], s69, v33
	v_mul_f32_e64 v10, |v168|, v17
	v_mul_f32_e32 v9, 0x3fb8aa3b, v10
	v_cndmask_b32_e64 v8, 0, v8, s[10:11]
	v_cmp_nlt_f32_e64 s[10:11], s70, v33
	v_fma_f32 v11, v10, s68, -v9
	v_rndne_f32_e32 v32, v9
	v_cndmask_b32_e64 v8, v185, v8, s[10:11]
	v_add_f32_e32 v8, 0x3d4ccccd, v8
	v_fmac_f32_e32 v11, 0x32a5705f, v10
	v_sub_f32_e32 v9, v9, v32
	v_mul_f32_e32 v8, v8, v71
	v_add_f32_e32 v9, v9, v11
	v_cndmask_b32_e64 v20, v8, 0, vcc
	v_exp_f32_e32 v11, v9
	v_cvt_i32_f32_e32 v32, v32
	v_bfe_u32 v8, v20, 16, 1
	v_add3_u32 v33, v20, v8, s71
	v_lshl_add_u64 v[8:9], v[12:13], 0, v[4:5]
	global_store_short_d16_hi v[8:9], v33, off
	v_mul_f32_e64 v9, |v168|, v93
	v_ldexp_f32 v8, v11, v32
	v_mul_f32_e32 v11, 0x3fb8aa3b, v9
	v_fma_f32 v32, v9, s68, -v11
	v_rndne_f32_e32 v33, v11
	v_fmac_f32_e32 v32, 0x32a5705f, v9
	v_sub_f32_e32 v11, v11, v33
	v_add_f32_e32 v11, v11, v32
	v_exp_f32_e32 v32, v11
	v_cvt_i32_f32_e32 v33, v33
	v_cmp_ngt_f32_e64 s[10:11], s69, v10
	s_nop 1
	v_cndmask_b32_e64 v8, 0, v8, s[10:11]
	v_cmp_nlt_f32_e64 s[10:11], s70, v10
	v_lshl_add_u64 v[10:11], v[12:13], 0, v[6:7]
	v_ldexp_f32 v12, v32, v33
	v_cndmask_b32_e64 v8, v185, v8, s[10:11]
	v_cmp_ngt_f32_e64 s[10:11], s69, v9
	v_mul_f32_e64 v32, |v168|, v95
	v_mul_f32_e32 v33, 0x3fb8aa3b, v32
	v_cndmask_b32_e64 v12, 0, v12, s[10:11]
	v_cmp_nlt_f32_e64 s[10:11], s70, v9
	v_fma_f32 v71, v32, s68, -v33
	v_fmac_f32_e32 v71, 0x32a5705f, v32
	v_cndmask_b32_e64 v9, v185, v12, s[10:11]
	v_pk_add_f32 v[8:9], v[8:9], s[96:97] op_sel_hi:[1,0]
	v_cmp_ngt_f32_e64 s[10:11], s69, v32
	v_pk_mul_f32 v[8:9], v[8:9], v[72:73]
	v_rndne_f32_e32 v72, v33
	v_sub_f32_e32 v33, v33, v72
	v_add_f32_e32 v33, v33, v71
	v_exp_f32_e32 v33, v33
	v_cvt_i32_f32_e32 v71, v72
	v_add_f32_e64 v12, |v20|, |v8|
	v_and_b32_sdwa v13, v9, v186 dst_sel:DWORD dst_unused:UNUSED_PAD src0_sel:WORD_1 src1_sel:DWORD
	v_and_b32_sdwa v20, v8, v186 dst_sel:DWORD dst_unused:UNUSED_PAD src0_sel:WORD_1 src1_sel:DWORD
	v_add3_u32 v13, v9, v13, s71
	v_add_f32_e64 v9, v12, |v9|
	v_ldexp_f32 v12, v33, v71
	v_add3_u32 v8, v8, v20, s71
	v_cndmask_b32_e64 v12, 0, v12, s[10:11]
	v_cmp_nlt_f32_e64 s[10:11], s70, v32
	v_perm_b32 v8, v13, v8, s72
	v_mul_f32_e64 v13, |v169|, v16
	v_cndmask_b32_e64 v12, v185, v12, s[10:11]
	v_add_f32_e32 v12, 0x3d4ccccd, v12
	v_mul_f32_e32 v32, 0x3fb8aa3b, v13
	v_mul_f32_e32 v12, v12, v67
	v_fma_f32 v33, v13, s68, -v32
	v_rndne_f32_e32 v67, v32
	v_fmac_f32_e32 v33, 0x32a5705f, v13
	v_sub_f32_e32 v32, v32, v67
	v_add_f32_e32 v32, v32, v33
	v_exp_f32_e32 v32, v32
	v_cvt_i32_f32_e32 v33, v67
	v_bfe_u32 v20, v12, 16, 1
	v_add3_u32 v20, v12, v20, s71
	global_store_short_d16_hi v[10:11], v20, off offset:6
	global_store_dword v[10:11], v8, off offset:2
	v_ldexp_f32 v8, v32, v33
	v_cmp_ngt_f32_e64 s[10:11], s69, v13
	v_mul_f32_e64 v10, |v169|, v17
	v_add_f32_e64 v12, v9, |v12|
	v_cndmask_b32_e64 v8, 0, v8, s[10:11]
	v_cmp_nlt_f32_e64 s[10:11], s70, v13
	v_mul_f32_e32 v9, 0x3fb8aa3b, v10
	v_fma_f32 v11, v10, s68, -v9
	v_cndmask_b32_e64 v8, v185, v8, s[10:11]
	v_rndne_f32_e32 v20, v9
	v_add_f32_e32 v8, 0x3d4ccccd, v8
	v_fmac_f32_e32 v11, 0x32a5705f, v10
	v_sub_f32_e32 v9, v9, v20
	v_mul_f32_e32 v8, v8, v70
	v_add_f32_e32 v9, v9, v11
	v_cndmask_b32_e64 v13, v8, 0, vcc
	v_exp_f32_e32 v11, v9
	v_cvt_i32_f32_e32 v20, v20
	v_bfe_u32 v8, v13, 16, 1
	v_add3_u32 v32, v13, v8, s71
	v_lshl_add_u64 v[8:9], v[14:15], 0, v[4:5]
	global_store_short_d16_hi v[8:9], v32, off
	v_mul_f32_e64 v9, |v169|, v93
	v_ldexp_f32 v8, v11, v20
	v_mul_f32_e32 v11, 0x3fb8aa3b, v9
	v_fma_f32 v20, v9, s68, -v11
	v_rndne_f32_e32 v32, v11
	v_fmac_f32_e32 v20, 0x32a5705f, v9
	v_sub_f32_e32 v11, v11, v32
	v_add_f32_e32 v11, v11, v20
	v_exp_f32_e32 v20, v11
	v_cvt_i32_f32_e32 v32, v32
	v_cmp_ngt_f32_e64 s[10:11], s69, v10
	s_nop 1
	v_cndmask_b32_e64 v8, 0, v8, s[10:11]
	v_cmp_nlt_f32_e64 s[10:11], s70, v10
	v_lshl_add_u64 v[10:11], v[14:15], 0, v[6:7]
	v_ldexp_f32 v14, v20, v32
	v_mul_f32_e64 v20, |v169|, v95
	v_mul_f32_e32 v32, 0x3fb8aa3b, v20
	v_fma_f32 v33, v20, s68, -v32
	v_rndne_f32_e32 v67, v32
	v_cndmask_b32_e64 v8, v185, v8, s[10:11]
	v_cmp_ngt_f32_e64 s[10:11], s69, v9
	v_fmac_f32_e32 v33, 0x32a5705f, v20
	v_sub_f32_e32 v32, v32, v67
	v_cndmask_b32_e64 v14, 0, v14, s[10:11]
	v_cmp_nlt_f32_e64 s[10:11], s70, v9
	v_add_f32_e32 v32, v32, v33
	v_exp_f32_e32 v32, v32
	v_cndmask_b32_e64 v9, v185, v14, s[10:11]
	v_cvt_i32_f32_e32 v33, v67
	v_pk_add_f32 v[8:9], v[8:9], s[96:97] op_sel_hi:[1,0]
	v_cmp_ngt_f32_e64 s[10:11], s69, v20
	v_pk_mul_f32 v[8:9], v[8:9], v[68:69]
	s_nop 0
	v_add_f32_e64 v13, |v13|, |v8|
	v_and_b32_sdwa v14, v9, v186 dst_sel:DWORD dst_unused:UNUSED_PAD src0_sel:WORD_1 src1_sel:DWORD
	v_add3_u32 v14, v9, v14, s71
	v_add_f32_e64 v9, v13, |v9|
	v_ldexp_f32 v13, v32, v33
	v_cndmask_b32_e64 v13, 0, v13, s[10:11]
	v_cmp_nlt_f32_e64 s[10:11], s70, v20
	v_and_b32_sdwa v15, v8, v186 dst_sel:DWORD dst_unused:UNUSED_PAD src0_sel:WORD_1 src1_sel:DWORD
	v_add3_u32 v8, v8, v15, s71
	v_cndmask_b32_e64 v13, v185, v13, s[10:11]
	v_add_f32_e32 v13, 0x3d4ccccd, v13
	v_mul_f32_e32 v13, v13, v66
	v_bfe_u32 v15, v13, 16, 1
	v_add3_u32 v15, v13, v15, s71
	v_perm_b32 v8, v14, v8, s72
	global_store_short_d16_hi v[10:11], v15, off offset:6
	global_store_dword v[10:11], v8, off offset:2
	v_add_f32_e64 v8, v9, |v13|
	v_mul_f32_e64 v10, |v170|, v16
	ds_write2st64_b32 v162, v12, v8 offset0:46 offset1:47
	v_mul_f32_e32 v8, 0x3fb8aa3b, v10
	v_fma_f32 v9, v10, s68, -v8
	v_rndne_f32_e32 v11, v8
	v_fmac_f32_e32 v9, 0x32a5705f, v10
	v_sub_f32_e32 v8, v8, v11
	v_add_f32_e32 v8, v8, v9
	v_exp_f32_e32 v12, v8
	v_cvt_i32_f32_e32 v11, v11
	v_cmp_ngt_f32_e64 s[10:11], s69, v10
	v_mul_f32_e64 v13, |v170|, v17
	v_lshlrev_b32_e32 v8, s14, v156
	v_ldexp_f32 v11, v12, v11
	v_cndmask_b32_e64 v11, 0, v11, s[10:11]
	v_cmp_nlt_f32_e64 s[10:11], s70, v10
	v_lshlrev_b32_e32 v20, 1, v8
	v_lshl_add_u64 v[8:9], s[12:13], 0, v[20:21]
	v_cndmask_b32_e64 v10, v185, v11, s[10:11]
	v_add_f32_e32 v10, 0x3d4ccccd, v10
	v_mul_f32_e32 v12, v10, v65
	v_mul_f32_e32 v10, 0x3fb8aa3b, v13
	v_fma_f32 v11, v13, s68, -v10
	v_rndne_f32_e32 v14, v10
	v_fmac_f32_e32 v11, 0x32a5705f, v13
	v_sub_f32_e32 v10, v10, v14
	v_add_f32_e32 v10, v10, v11
	v_exp_f32_e32 v15, v10
	v_cvt_i32_f32_e32 v14, v14
	v_cmp_ngt_f32_e64 s[10:11], s69, v13
	v_bfe_u32 v10, v12, 16, 1
	v_add3_u32 v20, v12, v10, s71
	v_ldexp_f32 v14, v15, v14
	v_cndmask_b32_e64 v14, 0, v14, s[10:11]
	v_cmp_nlt_f32_e64 s[10:11], s70, v13
	v_lshl_add_u64 v[10:11], v[8:9], 0, v[2:3]
	s_nop 0
	v_cndmask_b32_e64 v13, v185, v14, s[10:11]
	v_mul_f32_e64 v14, |v170|, v93
	v_mul_f32_e32 v15, 0x3fb8aa3b, v14
	v_fma_f32 v32, v14, s68, -v15
	v_rndne_f32_e32 v33, v15
	v_fmac_f32_e32 v32, 0x32a5705f, v14
	v_sub_f32_e32 v15, v15, v33
	v_add_f32_e32 v15, v15, v32
	v_exp_f32_e32 v15, v15
	v_cvt_i32_f32_e32 v32, v33
	v_add_f32_e32 v13, 0x3d4ccccd, v13
	v_mul_f32_e32 v13, v13, v61
	v_bfe_u32 v33, v13, 16, 1
	v_add_f32_e64 v61, |v12|, |v13|
	v_ldexp_f32 v12, v15, v32
	v_mul_f32_e64 v15, |v170|, v95
	v_add3_u32 v33, v13, v33, s71
	v_mul_f32_e32 v13, 0x3fb8aa3b, v15
	v_fma_f32 v32, v15, s68, -v13
	v_rndne_f32_e32 v65, v13
	v_fmac_f32_e32 v32, 0x32a5705f, v15
	v_sub_f32_e32 v13, v13, v65
	v_add_f32_e32 v13, v13, v32
	v_exp_f32_e32 v32, v13
	v_cvt_i32_f32_e32 v65, v65
	v_cmp_ngt_f32_e64 s[10:11], s69, v14
	s_nop 1
	v_cndmask_b32_e64 v12, 0, v12, s[10:11]
	v_cmp_nlt_f32_e64 s[10:11], s70, v14
	s_nop 1
	v_cndmask_b32_e64 v13, v185, v12, s[10:11]
	v_ldexp_f32 v12, v32, v65
	v_cmp_ngt_f32_e64 s[10:11], s69, v15
	s_nop 1
	v_cndmask_b32_e64 v12, 0, v12, s[10:11]
	v_cmp_nlt_f32_e64 s[10:11], s70, v15
	s_nop 1
	v_cndmask_b32_e64 v12, v185, v12, s[10:11]
	v_pk_add_f32 v[12:13], v[12:13], s[96:97] op_sel_hi:[1,0]
	s_nop 0
	v_pk_mul_f32 v[12:13], v[12:13], v[62:63]
	s_nop 0
	v_and_b32_sdwa v14, v13, v186 dst_sel:DWORD dst_unused:UNUSED_PAD src0_sel:WORD_1 src1_sel:DWORD
	v_and_b32_sdwa v15, v12, v186 dst_sel:DWORD dst_unused:UNUSED_PAD src0_sel:WORD_1 src1_sel:DWORD
	v_add_f32_e64 v32, v61, |v13|
	v_add3_u32 v15, v12, v15, s71
	v_add3_u32 v13, v13, v14, s71
	v_perm_b32 v14, v13, v15, s72
	v_perm_b32 v15, v20, v33, s72
	v_add_f32_e64 v61, v32, |v12|
	v_mul_f32_e64 v12, |v171|, v16
	global_store_dwordx2 v[10:11], v[14:15], off offset:-6
	v_mul_f32_e32 v10, 0x3fb8aa3b, v12
	v_fma_f32 v11, v12, s68, -v10
	v_rndne_f32_e32 v13, v10
	v_fmac_f32_e32 v11, 0x32a5705f, v12
	v_sub_f32_e32 v10, v10, v13
	v_add_f32_e32 v10, v10, v11
	v_exp_f32_e32 v14, v10
	v_cvt_i32_f32_e32 v13, v13
	v_cmp_ngt_f32_e64 s[10:11], s69, v12
	v_lshlrev_b32_e32 v10, s14, v157
	v_mul_f32_e64 v15, |v171|, v17
	v_ldexp_f32 v13, v14, v13
	v_cndmask_b32_e64 v13, 0, v13, s[10:11]
	v_cmp_nlt_f32_e64 s[10:11], s70, v12
	v_lshlrev_b32_e32 v20, 1, v10
	v_lshl_add_u64 v[10:11], s[12:13], 0, v[20:21]
	v_cndmask_b32_e64 v12, v185, v13, s[10:11]
	v_add_f32_e32 v12, 0x3d4ccccd, v12
	v_mul_f32_e32 v14, v12, v64
	v_mul_f32_e32 v12, 0x3fb8aa3b, v15
	v_fma_f32 v13, v15, s68, -v12
	v_rndne_f32_e32 v20, v12
	v_fmac_f32_e32 v13, 0x32a5705f, v15
	v_sub_f32_e32 v12, v12, v20
	v_add_f32_e32 v12, v12, v13
	v_exp_f32_e32 v32, v12
	v_cvt_i32_f32_e32 v20, v20
	v_cmp_ngt_f32_e64 s[10:11], s69, v15
	v_bfe_u32 v12, v14, 16, 1
	v_add3_u32 v33, v14, v12, s71
	v_ldexp_f32 v20, v32, v20
	v_cndmask_b32_e64 v20, 0, v20, s[10:11]
	v_cmp_nlt_f32_e64 s[10:11], s70, v15
	v_lshl_add_u64 v[12:13], v[10:11], 0, v[2:3]
	s_nop 0
	v_cndmask_b32_e64 v15, v185, v20, s[10:11]
	v_mul_f32_e64 v20, |v171|, v93
	v_add_f32_e32 v15, 0x3d4ccccd, v15
	v_mul_f32_e32 v32, 0x3fb8aa3b, v20
	v_mul_f32_e32 v15, v15, v60
	v_fma_f32 v60, v20, s68, -v32
	v_rndne_f32_e32 v62, v32
	v_fmac_f32_e32 v60, 0x32a5705f, v20
	v_sub_f32_e32 v32, v32, v62
	v_add_f32_e32 v32, v32, v60
	v_exp_f32_e32 v32, v32
	v_cvt_i32_f32_e32 v60, v62
	v_bfe_u32 v62, v15, 16, 1
	v_add_f32_e64 v63, |v14|, |v15|
	v_add3_u32 v62, v15, v62, s71
	v_ldexp_f32 v14, v32, v60
	v_mul_f32_e64 v32, |v171|, v95
	v_mul_f32_e32 v15, 0x3fb8aa3b, v32
	v_fma_f32 v60, v32, s68, -v15
	v_rndne_f32_e32 v64, v15
	v_fmac_f32_e32 v60, 0x32a5705f, v32
	v_sub_f32_e32 v15, v15, v64
	v_add_f32_e32 v15, v15, v60
	v_exp_f32_e32 v60, v15
	v_cvt_i32_f32_e32 v64, v64
	v_cmp_ngt_f32_e64 s[10:11], s69, v20
	v_perm_b32 v33, v33, v62, s72
	s_nop 0
	v_cndmask_b32_e64 v14, 0, v14, s[10:11]
	v_cmp_nlt_f32_e64 s[10:11], s70, v20
	s_nop 1
	v_cndmask_b32_e64 v15, v185, v14, s[10:11]
	v_ldexp_f32 v14, v60, v64
	v_cmp_ngt_f32_e64 s[10:11], s69, v32
	s_nop 1
	v_cndmask_b32_e64 v14, 0, v14, s[10:11]
	v_cmp_nlt_f32_e64 s[10:11], s70, v32
	s_nop 1
	v_cndmask_b32_e64 v14, v185, v14, s[10:11]
	v_pk_add_f32 v[14:15], v[14:15], s[96:97] op_sel_hi:[1,0]
	s_nop 0
	v_pk_mul_f32 v[14:15], v[14:15], v[58:59]
	s_nop 0
	v_and_b32_sdwa v32, v15, v186 dst_sel:DWORD dst_unused:UNUSED_PAD src0_sel:WORD_1 src1_sel:DWORD
	v_and_b32_sdwa v58, v14, v186 dst_sel:DWORD dst_unused:UNUSED_PAD src0_sel:WORD_1 src1_sel:DWORD
	v_add_f32_e64 v20, v63, |v15|
	v_add3_u32 v58, v14, v58, s71
	v_add3_u32 v15, v15, v32, s71
	v_perm_b32 v32, v15, v58, s72
	global_store_dwordx2 v[12:13], v[32:33], off offset:-6
	v_add_f32_e64 v12, v20, |v14|
	v_mul_f32_e64 v14, |v172|, v16
	ds_write2st64_b32 v162, v61, v12 offset0:48 offset1:49
	v_mul_f32_e32 v12, 0x3fb8aa3b, v14
	v_fma_f32 v13, v14, s68, -v12
	v_rndne_f32_e32 v15, v12
	v_fmac_f32_e32 v13, 0x32a5705f, v14
	v_sub_f32_e32 v12, v12, v15
	v_add_f32_e32 v12, v12, v13
	v_exp_f32_e32 v32, v12
	v_cvt_i32_f32_e32 v15, v15
	v_cmp_ngt_f32_e64 s[10:11], s69, v14
	v_lshlrev_b32_e32 v12, s14, v158
	v_lshlrev_b32_e32 v20, 1, v12
	v_ldexp_f32 v15, v32, v15
	v_cndmask_b32_e64 v15, 0, v15, s[10:11]
	v_cmp_nlt_f32_e64 s[10:11], s70, v14
	v_mul_f32_e64 v32, |v172|, v17
	v_lshl_add_u64 v[12:13], s[12:13], 0, v[20:21]
	v_cndmask_b32_e64 v14, v185, v15, s[10:11]
	v_add_f32_e32 v14, 0x3d4ccccd, v14
	v_mul_f32_e32 v20, v14, v57
	v_mul_f32_e32 v14, 0x3fb8aa3b, v32
	v_fma_f32 v15, v32, s68, -v14
	v_rndne_f32_e32 v33, v14
	v_fmac_f32_e32 v15, 0x32a5705f, v32
	v_sub_f32_e32 v14, v14, v33
	v_add_f32_e32 v14, v14, v15
	v_exp_f32_e32 v57, v14
	v_cvt_i32_f32_e32 v33, v33
	v_cmp_ngt_f32_e64 s[10:11], s69, v32
	v_bfe_u32 v14, v20, 16, 1
	v_add3_u32 v58, v20, v14, s71
	v_ldexp_f32 v33, v57, v33
	v_cndmask_b32_e64 v33, 0, v33, s[10:11]
	v_cmp_nlt_f32_e64 s[10:11], s70, v32
	v_lshl_add_u64 v[14:15], v[12:13], 0, v[2:3]
	s_nop 0
	v_cndmask_b32_e64 v32, v185, v33, s[10:11]
	v_add_f32_e32 v32, 0x3d4ccccd, v32
	v_mul_f32_e64 v33, |v172|, v93
	v_mul_f32_e32 v32, v32, v53
	v_mul_f32_e32 v53, 0x3fb8aa3b, v33
	v_fma_f32 v57, v33, s68, -v53
	v_rndne_f32_e32 v59, v53
	v_fmac_f32_e32 v57, 0x32a5705f, v33
	v_sub_f32_e32 v53, v53, v59
	v_add_f32_e32 v53, v53, v57
	v_exp_f32_e32 v53, v53
	v_cvt_i32_f32_e32 v57, v59
	v_bfe_u32 v59, v32, 16, 1
	v_add3_u32 v59, v32, v59, s71
	v_add_f32_e64 v20, |v20|, |v32|
	v_ldexp_f32 v32, v53, v57
	v_mul_f32_e64 v53, |v172|, v95
	v_mul_f32_e32 v57, 0x3fb8aa3b, v53
	v_fma_f32 v60, v53, s68, -v57
	v_rndne_f32_e32 v61, v57
	v_fmac_f32_e32 v60, 0x32a5705f, v53
	v_sub_f32_e32 v57, v57, v61
	v_add_f32_e32 v57, v57, v60
	v_exp_f32_e32 v57, v57
	v_cvt_i32_f32_e32 v60, v61
	v_cmp_ngt_f32_e64 s[10:11], s69, v33
	s_nop 1
	v_cndmask_b32_e64 v32, 0, v32, s[10:11]
	v_cmp_nlt_f32_e64 s[10:11], s70, v33
	s_nop 1
	v_cndmask_b32_e64 v33, v185, v32, s[10:11]
	v_ldexp_f32 v32, v57, v60
	v_cmp_ngt_f32_e64 s[10:11], s69, v53
	s_nop 1
	v_cndmask_b32_e64 v32, 0, v32, s[10:11]
	v_cmp_nlt_f32_e64 s[10:11], s70, v53
	s_nop 1
	v_cndmask_b32_e64 v32, v185, v32, s[10:11]
	v_pk_add_f32 v[32:33], v[32:33], s[96:97] op_sel_hi:[1,0]
	s_nop 0
	v_pk_mul_f32 v[32:33], v[32:33], v[54:55]
	v_perm_b32 v55, v58, v59, s72
	v_and_b32_sdwa v53, v33, v186 dst_sel:DWORD dst_unused:UNUSED_PAD src0_sel:WORD_1 src1_sel:DWORD
	v_and_b32_sdwa v54, v32, v186 dst_sel:DWORD dst_unused:UNUSED_PAD src0_sel:WORD_1 src1_sel:DWORD
	v_add_f32_e64 v20, v20, |v33|
	v_add3_u32 v54, v32, v54, s71
	v_add3_u32 v33, v33, v53, s71
	v_perm_b32 v54, v33, v54, s72
	v_add_f32_e64 v53, v20, |v32|
	v_mul_f32_e64 v32, |v173|, v16
	global_store_dwordx2 v[14:15], v[54:55], off offset:-6
	v_mul_f32_e32 v14, 0x3fb8aa3b, v32
	v_fma_f32 v15, v32, s68, -v14
	v_rndne_f32_e32 v20, v14
	v_fmac_f32_e32 v15, 0x32a5705f, v32
	v_sub_f32_e32 v14, v14, v20
	v_add_f32_e32 v14, v14, v15
	v_exp_f32_e32 v33, v14
	v_cvt_i32_f32_e32 v54, v20
	v_lshlrev_b32_e32 v14, s14, v159
	v_lshlrev_b32_e32 v20, 1, v14
	v_lshl_add_u64 v[14:15], s[12:13], 0, v[20:21]
	v_ldexp_f32 v20, v33, v54
	v_cmp_ngt_f32_e64 s[10:11], s69, v32
	v_lshl_add_u64 v[2:3], v[14:15], 0, v[2:3]
	s_nop 0
	v_cndmask_b32_e64 v20, 0, v20, s[10:11]
	v_cmp_nlt_f32_e64 s[10:11], s70, v32
	v_mul_f32_e64 v32, |v173|, v17
	v_mul_f32_e32 v33, 0x3fb8aa3b, v32
	v_fma_f32 v54, v32, s68, -v33
	v_rndne_f32_e32 v55, v33
	v_fmac_f32_e32 v54, 0x32a5705f, v32
	v_sub_f32_e32 v33, v33, v55
	v_add_f32_e32 v33, v33, v54
	v_exp_f32_e32 v33, v33
	v_cvt_i32_f32_e32 v54, v55
	v_cndmask_b32_e64 v20, v185, v20, s[10:11]
	v_cmp_ngt_f32_e64 s[10:11], s69, v32
	v_add_f32_e32 v20, 0x3d4ccccd, v20
	v_ldexp_f32 v33, v33, v54
	v_cndmask_b32_e64 v33, 0, v33, s[10:11]
	v_cmp_nlt_f32_e64 s[10:11], s70, v32
	v_mul_f32_e32 v20, v20, v56
	v_bfe_u32 v55, v20, 16, 1
	v_cndmask_b32_e64 v32, v185, v33, s[10:11]
	v_add_f32_e32 v32, 0x3d4ccccd, v32
	v_mul_f32_e64 v33, |v173|, v93
	v_mul_f32_e32 v32, v32, v52
	v_mul_f32_e32 v52, 0x3fb8aa3b, v33
	v_fma_f32 v54, v33, s68, -v52
	v_rndne_f32_e32 v56, v52
	v_fmac_f32_e32 v54, 0x32a5705f, v33
	v_sub_f32_e32 v52, v52, v56
	v_add_f32_e32 v52, v52, v54
	v_exp_f32_e32 v52, v52
	v_cvt_i32_f32_e32 v54, v56
	v_bfe_u32 v56, v32, 16, 1
	v_add3_u32 v55, v20, v55, s71
	v_add3_u32 v56, v32, v56, s71
	v_add_f32_e64 v20, |v20|, |v32|
	v_ldexp_f32 v32, v52, v54
	v_mul_f32_e64 v52, |v173|, v95
	v_mul_f32_e32 v54, 0x3fb8aa3b, v52
	v_fma_f32 v57, v52, s68, -v54
	v_rndne_f32_e32 v58, v54
	v_fmac_f32_e32 v57, 0x32a5705f, v52
	v_sub_f32_e32 v54, v54, v58
	v_add_f32_e32 v54, v54, v57
	v_exp_f32_e32 v54, v54
	v_cvt_i32_f32_e32 v57, v58
	v_cmp_ngt_f32_e64 s[10:11], s69, v33
	s_nop 1
	v_cndmask_b32_e64 v32, 0, v32, s[10:11]
	v_cmp_nlt_f32_e64 s[10:11], s70, v33
	s_nop 1
	v_cndmask_b32_e64 v33, v185, v32, s[10:11]
	v_ldexp_f32 v32, v54, v57
	v_cmp_ngt_f32_e64 s[10:11], s69, v52
	s_nop 1
	v_cndmask_b32_e64 v32, 0, v32, s[10:11]
	v_cmp_nlt_f32_e64 s[10:11], s70, v52
	s_nop 1
	v_cndmask_b32_e64 v32, v185, v32, s[10:11]
	v_pk_add_f32 v[32:33], v[32:33], s[96:97] op_sel_hi:[1,0]
	s_nop 0
	v_pk_mul_f32 v[32:33], v[32:33], v[50:51]
	s_nop 0
	v_and_b32_sdwa v50, v33, v186 dst_sel:DWORD dst_unused:UNUSED_PAD src0_sel:WORD_1 src1_sel:DWORD
	v_and_b32_sdwa v51, v32, v186 dst_sel:DWORD dst_unused:UNUSED_PAD src0_sel:WORD_1 src1_sel:DWORD
	v_add_f32_e64 v20, v20, |v33|
	v_add3_u32 v51, v32, v51, s71
	v_add3_u32 v33, v33, v50, s71
	v_perm_b32 v50, v33, v51, s72
	v_mul_f32_e64 v33, |v174|, v16
	v_mul_f32_e32 v52, 0x3fb8aa3b, v33
	v_perm_b32 v51, v55, v56, s72
	v_fma_f32 v54, v33, s68, -v52
	v_rndne_f32_e32 v55, v52
	v_fmac_f32_e32 v54, 0x32a5705f, v33
	v_sub_f32_e32 v52, v52, v55
	v_add_f32_e32 v52, v52, v54
	v_exp_f32_e32 v52, v52
	v_cvt_i32_f32_e32 v54, v55
	global_store_dwordx2 v[2:3], v[50:51], off offset:-6
	v_add_f32_e64 v2, v20, |v32|
	ds_write2st64_b32 v162, v53, v2 offset0:50 offset1:51
	v_ldexp_f32 v2, v52, v54
	v_cmp_ngt_f32_e64 s[10:11], s69, v33
	v_mul_f32_e64 v32, |v174|, v17
	v_mul_f32_e32 v3, 0x3fb8aa3b, v32
	v_cndmask_b32_e64 v2, 0, v2, s[10:11]
	v_cmp_nlt_f32_e64 s[10:11], s70, v33
	v_fma_f32 v33, v32, s68, -v3
	v_fmac_f32_e32 v33, 0x32a5705f, v32
	v_cndmask_b32_e64 v2, v185, v2, s[10:11]
	v_add_f32_e32 v2, 0x3d4ccccd, v2
	v_mul_f32_e32 v2, v2, v47
	v_rndne_f32_e32 v47, v3
	v_sub_f32_e32 v3, v3, v47
	v_add_f32_e32 v3, v3, v33
	v_cndmask_b32_e64 v20, v2, 0, vcc
	v_exp_f32_e32 v33, v3
	v_cvt_i32_f32_e32 v47, v47
	v_bfe_u32 v2, v20, 16, 1
	v_add3_u32 v50, v20, v2, s71
	v_lshl_add_u64 v[2:3], v[8:9], 0, v[4:5]
	global_store_short_d16_hi v[2:3], v50, off
	v_mul_f32_e64 v3, |v174|, v93
	v_ldexp_f32 v2, v33, v47
	v_mul_f32_e32 v33, 0x3fb8aa3b, v3
	v_fma_f32 v47, v3, s68, -v33
	v_rndne_f32_e32 v50, v33
	v_fmac_f32_e32 v47, 0x32a5705f, v3
	v_sub_f32_e32 v33, v33, v50
	v_add_f32_e32 v33, v33, v47
	v_exp_f32_e32 v33, v33
	v_cvt_i32_f32_e32 v47, v50
	v_cmp_ngt_f32_e64 s[10:11], s69, v32
	v_lshl_add_u64 v[8:9], v[8:9], 0, v[6:7]
	s_nop 0
	v_cndmask_b32_e64 v2, 0, v2, s[10:11]
	v_cmp_nlt_f32_e64 s[10:11], s70, v32
	v_ldexp_f32 v32, v33, v47
	v_mul_f32_e64 v47, |v174|, v95
	v_cndmask_b32_e64 v2, v185, v2, s[10:11]
	v_cmp_ngt_f32_e64 s[10:11], s69, v3
	s_nop 1
	v_cndmask_b32_e64 v32, 0, v32, s[10:11]
	v_cmp_nlt_f32_e64 s[10:11], s70, v3
	s_nop 1
	v_cndmask_b32_e64 v3, v185, v32, s[10:11]
	v_pk_add_f32 v[2:3], v[2:3], s[96:97] op_sel_hi:[1,0]
	v_cmp_ngt_f32_e64 s[10:11], s69, v47
	v_pk_mul_f32 v[2:3], v[2:3], v[48:49]
	v_mul_f32_e32 v48, 0x3fb8aa3b, v47
	v_fma_f32 v49, v47, s68, -v48
	v_rndne_f32_e32 v50, v48
	v_fmac_f32_e32 v49, 0x32a5705f, v47
	v_sub_f32_e32 v48, v48, v50
	v_add_f32_e32 v48, v48, v49
	v_exp_f32_e32 v48, v48
	v_cvt_i32_f32_e32 v49, v50
	v_add_f32_e64 v20, |v20|, |v2|
	v_and_b32_sdwa v32, v3, v186 dst_sel:DWORD dst_unused:UNUSED_PAD src0_sel:WORD_1 src1_sel:DWORD
	v_add3_u32 v32, v3, v32, s71
	v_add_f32_e64 v3, v20, |v3|
	v_ldexp_f32 v20, v48, v49
	v_and_b32_sdwa v33, v2, v186 dst_sel:DWORD dst_unused:UNUSED_PAD src0_sel:WORD_1 src1_sel:DWORD
	v_cndmask_b32_e64 v20, 0, v20, s[10:11]
	v_cmp_nlt_f32_e64 s[10:11], s70, v47
	v_add3_u32 v2, v2, v33, s71
	v_perm_b32 v2, v32, v2, s72
	v_cndmask_b32_e64 v20, v185, v20, s[10:11]
	v_add_f32_e32 v20, 0x3d4ccccd, v20
	v_mul_f32_e64 v32, |v175|, v16
	v_mul_f32_e32 v20, v20, v43
	v_mul_f32_e32 v43, 0x3fb8aa3b, v32
	v_fma_f32 v47, v32, s68, -v43
	v_rndne_f32_e32 v48, v43
	v_fmac_f32_e32 v47, 0x32a5705f, v32
	v_sub_f32_e32 v43, v43, v48
	v_add_f32_e32 v43, v43, v47
	v_exp_f32_e32 v43, v43
	v_cvt_i32_f32_e32 v47, v48
	v_bfe_u32 v33, v20, 16, 1
	v_add3_u32 v33, v20, v33, s71
	global_store_dword v[8:9], v2, off offset:2
	global_store_short_d16_hi v[8:9], v33, off offset:6
	v_ldexp_f32 v2, v43, v47
	v_cmp_ngt_f32_e64 s[10:11], s69, v32
	v_mul_f32_e64 v8, |v175|, v17
	v_add_f32_e64 v20, v3, |v20|
	v_cndmask_b32_e64 v2, 0, v2, s[10:11]
	v_cmp_nlt_f32_e64 s[10:11], s70, v32
	v_mul_f32_e32 v3, 0x3fb8aa3b, v8
	v_fma_f32 v9, v8, s68, -v3
	v_cndmask_b32_e64 v2, v185, v2, s[10:11]
	v_rndne_f32_e32 v33, v3
	v_add_f32_e32 v2, 0x3d4ccccd, v2
	v_fmac_f32_e32 v9, 0x32a5705f, v8
	v_sub_f32_e32 v3, v3, v33
	v_mul_f32_e32 v2, v2, v46
	v_add_f32_e32 v3, v3, v9
	v_cndmask_b32_e64 v32, v2, 0, vcc
	v_exp_f32_e32 v9, v3
	v_cvt_i32_f32_e32 v33, v33
	v_bfe_u32 v2, v32, 16, 1
	v_add3_u32 v43, v32, v2, s71
	v_lshl_add_u64 v[2:3], v[10:11], 0, v[4:5]
	global_store_short_d16_hi v[2:3], v43, off
	v_mul_f32_e64 v3, |v175|, v93
	v_ldexp_f32 v2, v9, v33
	v_mul_f32_e32 v9, 0x3fb8aa3b, v3
	v_fma_f32 v33, v3, s68, -v9
	v_rndne_f32_e32 v43, v9
	v_fmac_f32_e32 v33, 0x32a5705f, v3
	v_sub_f32_e32 v9, v9, v43
	v_add_f32_e32 v9, v9, v33
	v_exp_f32_e32 v33, v9
	v_cvt_i32_f32_e32 v43, v43
	v_cmp_ngt_f32_e64 s[10:11], s69, v8
	s_nop 1
	v_cndmask_b32_e64 v2, 0, v2, s[10:11]
	v_cmp_nlt_f32_e64 s[10:11], s70, v8
	v_lshl_add_u64 v[8:9], v[10:11], 0, v[6:7]
	v_ldexp_f32 v10, v33, v43
	v_cndmask_b32_e64 v2, v185, v2, s[10:11]
	v_cmp_ngt_f32_e64 s[10:11], s69, v3
	v_mul_f32_e64 v33, |v175|, v95
	v_mul_f32_e32 v43, 0x3fb8aa3b, v33
	v_cndmask_b32_e64 v10, 0, v10, s[10:11]
	v_cmp_nlt_f32_e64 s[10:11], s70, v3
	s_nop 1
	v_cndmask_b32_e64 v3, v185, v10, s[10:11]
	v_pk_add_f32 v[2:3], v[2:3], s[96:97] op_sel_hi:[1,0]
	v_cmp_ngt_f32_e64 s[10:11], s69, v33
	v_pk_mul_f32 v[2:3], v[2:3], v[44:45]
	v_fma_f32 v44, v33, s68, -v43
	v_rndne_f32_e32 v45, v43
	v_fmac_f32_e32 v44, 0x32a5705f, v33
	v_sub_f32_e32 v43, v43, v45
	v_add_f32_e32 v43, v43, v44
	v_exp_f32_e32 v43, v43
	v_cvt_i32_f32_e32 v44, v45
	v_add_f32_e64 v10, |v32|, |v2|
	v_and_b32_sdwa v11, v3, v186 dst_sel:DWORD dst_unused:UNUSED_PAD src0_sel:WORD_1 src1_sel:DWORD
	v_and_b32_sdwa v32, v2, v186 dst_sel:DWORD dst_unused:UNUSED_PAD src0_sel:WORD_1 src1_sel:DWORD
	v_add3_u32 v2, v2, v32, s71
	v_add3_u32 v11, v3, v11, s71
	v_add_f32_e64 v3, v10, |v3|
	v_ldexp_f32 v10, v43, v44
	v_cndmask_b32_e64 v10, 0, v10, s[10:11]
	v_cmp_nlt_f32_e64 s[10:11], s70, v33
	v_perm_b32 v2, v11, v2, s72
	global_store_dword v[8:9], v2, off offset:2
	v_cndmask_b32_e64 v10, v185, v10, s[10:11]
	v_mul_f32_e64 v2, |v176|, v16
	v_add_f32_e32 v10, 0x3d4ccccd, v10
	v_mul_f32_e32 v11, 0x3fb8aa3b, v2
	v_mul_f32_e32 v10, v10, v42
	v_fma_f32 v33, v2, s68, -v11
	v_rndne_f32_e32 v42, v11
	v_fmac_f32_e32 v33, 0x32a5705f, v2
	v_sub_f32_e32 v11, v11, v42
	v_add_f32_e32 v11, v11, v33
	v_exp_f32_e32 v11, v11
	v_cvt_i32_f32_e32 v33, v42
	v_bfe_u32 v32, v10, 16, 1
	v_add_f32_e64 v3, v3, |v10|
	v_add3_u32 v32, v10, v32, s71
	ds_write2st64_b32 v162, v20, v3 offset0:52 offset1:53
	v_ldexp_f32 v3, v11, v33
	v_cmp_ngt_f32_e64 s[10:11], s69, v2
	global_store_short_d16_hi v[8:9], v32, off offset:6
	v_mul_f32_e64 v8, |v176|, v17
	v_cndmask_b32_e64 v3, 0, v3, s[10:11]
	v_cmp_nlt_f32_e64 s[10:11], s70, v2
	s_nop 1
	v_cndmask_b32_e64 v2, v185, v3, s[10:11]
	v_mul_f32_e32 v3, 0x3fb8aa3b, v8
	v_fma_f32 v9, v8, s68, -v3
	v_rndne_f32_e32 v11, v3
	v_add_f32_e32 v2, 0x3d4ccccd, v2
	v_fmac_f32_e32 v9, 0x32a5705f, v8
	v_sub_f32_e32 v3, v3, v11
	v_mul_f32_e32 v2, v2, v39
	v_add_f32_e32 v3, v3, v9
	v_cndmask_b32_e64 v10, v2, 0, vcc
	v_exp_f32_e32 v9, v3
	v_cvt_i32_f32_e32 v11, v11
	v_bfe_u32 v2, v10, 16, 1
	v_add3_u32 v20, v10, v2, s71
	v_lshl_add_u64 v[2:3], v[12:13], 0, v[4:5]
	global_store_short_d16_hi v[2:3], v20, off
	v_mul_f32_e64 v3, |v176|, v93
	v_ldexp_f32 v2, v9, v11
	v_mul_f32_e32 v9, 0x3fb8aa3b, v3
	v_fma_f32 v11, v3, s68, -v9
	v_rndne_f32_e32 v20, v9
	v_fmac_f32_e32 v11, 0x32a5705f, v3
	v_sub_f32_e32 v9, v9, v20
	v_add_f32_e32 v9, v9, v11
	v_exp_f32_e32 v11, v9
	v_cvt_i32_f32_e32 v20, v20
	v_cmp_ngt_f32_e64 s[10:11], s69, v8
	v_ldexp_f32 v11, v11, v20
	s_nop 0
	v_cndmask_b32_e64 v2, 0, v2, s[10:11]
	v_cmp_nlt_f32_e64 s[10:11], s70, v8
	v_lshl_add_u64 v[8:9], v[12:13], 0, v[6:7]
	v_mul_f32_e64 v13, |v176|, v95
	v_mul_f32_e32 v20, 0x3fb8aa3b, v13
	v_cndmask_b32_e64 v2, v185, v2, s[10:11]
	v_cmp_ngt_f32_e64 s[10:11], s69, v3
	v_fma_f32 v32, v13, s68, -v20
	v_rndne_f32_e32 v33, v20
	v_cndmask_b32_e64 v11, 0, v11, s[10:11]
	v_cmp_nlt_f32_e64 s[10:11], s70, v3
	v_fmac_f32_e32 v32, 0x32a5705f, v13
	v_sub_f32_e32 v20, v20, v33
	v_cndmask_b32_e64 v3, v185, v11, s[10:11]
	v_add_f32_e32 v20, v20, v32
	v_pk_add_f32 v[2:3], v[2:3], s[96:97] op_sel_hi:[1,0]
	v_exp_f32_e32 v20, v20
	v_cvt_i32_f32_e32 v32, v33
	v_pk_mul_f32 v[2:3], v[2:3], v[40:41]
	v_cmp_ngt_f32_e64 s[10:11], s69, v13
	v_and_b32_sdwa v11, v3, v186 dst_sel:DWORD dst_unused:UNUSED_PAD src0_sel:WORD_1 src1_sel:DWORD
	v_and_b32_sdwa v12, v2, v186 dst_sel:DWORD dst_unused:UNUSED_PAD src0_sel:WORD_1 src1_sel:DWORD
	v_add_f32_e64 v10, |v10|, |v2|
	v_add3_u32 v2, v2, v12, s71
	v_add3_u32 v11, v3, v11, s71
	v_add_f32_e64 v3, v10, |v3|
	v_ldexp_f32 v10, v20, v32
	v_perm_b32 v2, v11, v2, s72
	v_mul_f32_e64 v11, |v160|, v16
	v_cndmask_b32_e64 v10, 0, v10, s[10:11]
	v_cmp_nlt_f32_e64 s[10:11], s70, v13
	v_mul_f32_e32 v13, 0x3fb8aa3b, v11
	v_fma_f32 v16, v11, s68, -v13
	v_rndne_f32_e32 v20, v13
	v_fmac_f32_e32 v16, 0x32a5705f, v11
	v_sub_f32_e32 v13, v13, v20
	v_cndmask_b32_e64 v10, v185, v10, s[10:11]
	v_add_f32_e32 v13, v13, v16
	v_add_f32_e32 v10, 0x3d4ccccd, v10
	v_exp_f32_e32 v13, v13
	v_cvt_i32_f32_e32 v16, v20
	v_mul_f32_e32 v10, v10, v37
	v_bfe_u32 v12, v10, 16, 1
	v_add3_u32 v12, v10, v12, s71
	global_store_short_d16_hi v[8:9], v12, off offset:6
	global_store_dword v[8:9], v2, off offset:2
	v_ldexp_f32 v2, v13, v16
	v_cmp_ngt_f32_e64 s[10:11], s69, v11
	v_add_f32_e64 v8, v3, |v10|
	v_mul_f32_e64 v10, |v160|, v17
	v_cndmask_b32_e64 v2, 0, v2, s[10:11]
	v_cmp_nlt_f32_e64 s[10:11], s70, v11
	v_mul_f32_e32 v3, 0x3fb8aa3b, v10
	v_fma_f32 v11, v10, s68, -v3
	v_cndmask_b32_e64 v2, v185, v2, s[10:11]
	v_add_f32_e32 v2, 0x3d4ccccd, v2
	v_rndne_f32_e32 v12, v3
	v_mul_f32_e32 v2, v2, v38
	v_fmac_f32_e32 v11, 0x32a5705f, v10
	v_sub_f32_e32 v3, v3, v12
	v_cndmask_b32_e64 v9, v2, 0, vcc
	v_add_f32_e32 v3, v3, v11
	v_bfe_u32 v2, v9, 16, 1
	v_exp_f32_e32 v11, v3
	v_cvt_i32_f32_e32 v12, v12
	v_add3_u32 v13, v9, v2, s71
	v_lshl_add_u64 v[2:3], v[14:15], 0, v[4:5]
	global_store_short_d16_hi v[2:3], v13, off
	v_mul_f32_e64 v3, |v160|, v93
	v_mul_f32_e32 v4, 0x3fb8aa3b, v3
	v_ldexp_f32 v2, v11, v12
	v_fma_f32 v5, v3, s68, -v4
	v_rndne_f32_e32 v11, v4
	v_fmac_f32_e32 v5, 0x32a5705f, v3
	v_sub_f32_e32 v4, v4, v11
	v_add_f32_e32 v4, v4, v5
	v_exp_f32_e32 v12, v4
	v_cvt_i32_f32_e32 v11, v11
	v_cmp_ngt_f32_e32 vcc, s69, v10
	v_lshl_add_u64 v[4:5], v[14:15], 0, v[6:7]
	v_ldexp_f32 v6, v12, v11
	v_cndmask_b32_e32 v2, 0, v2, vcc
	v_cmp_nlt_f32_e32 vcc, s70, v10
	v_mul_f32_e64 v10, |v160|, v95
	v_mul_f32_e32 v11, 0x3fb8aa3b, v10
	v_fma_f32 v12, v10, s68, -v11
	v_rndne_f32_e32 v13, v11
	v_cndmask_b32_e32 v2, v185, v2, vcc
	v_cmp_ngt_f32_e32 vcc, s69, v3
	v_fmac_f32_e32 v12, 0x32a5705f, v10
	v_sub_f32_e32 v11, v11, v13
	v_cndmask_b32_e32 v6, 0, v6, vcc
	v_cmp_nlt_f32_e32 vcc, s70, v3
	v_add_f32_e32 v11, v11, v12
	v_exp_f32_e32 v11, v11
	v_cndmask_b32_e32 v3, v185, v6, vcc
	v_cvt_i32_f32_e32 v12, v13
	v_pk_add_f32 v[2:3], v[2:3], s[96:97] op_sel_hi:[1,0]
	v_cmp_ngt_f32_e32 vcc, s69, v10
	v_pk_mul_f32 v[2:3], v[2:3], v[34:35]
	s_nop 0
	v_add_f32_e64 v6, |v9|, |v2|
	v_and_b32_sdwa v7, v3, v186 dst_sel:DWORD dst_unused:UNUSED_PAD src0_sel:WORD_1 src1_sel:DWORD
	v_add3_u32 v7, v3, v7, s71
	v_add_f32_e64 v3, v6, |v3|
	v_ldexp_f32 v6, v11, v12
	v_cndmask_b32_e32 v6, 0, v6, vcc
	v_cmp_nlt_f32_e32 vcc, s70, v10
	v_and_b32_sdwa v9, v2, v186 dst_sel:DWORD dst_unused:UNUSED_PAD src0_sel:WORD_1 src1_sel:DWORD
	v_add3_u32 v2, v2, v9, s71
	v_cndmask_b32_e32 v6, v185, v6, vcc
	v_add_f32_e32 v6, 0x3d4ccccd, v6
	v_mul_f32_e32 v6, v6, v36
	v_bfe_u32 v9, v6, 16, 1
	v_perm_b32 v2, v7, v2, s72
	v_add3_u32 v9, v6, v9, s71
	global_store_dword v[4:5], v2, off offset:2
	global_store_short_d16_hi v[4:5], v9, off offset:6
	v_add_f32_e64 v2, v3, |v6|
	ds_write2st64_b32 v162, v8, v2 offset0:54 offset1:55
	s_waitcnt lgkmcnt(0)
	s_barrier
	s_and_saveexec_b64 s[10:11], s[4:5]
	s_cbranch_execz .LBB0_45
	s_lshl_b32 s14, s6, 10
	s_and_b64 s[12:13], s[18:19], exec
	s_cselect_b32 s12, 0x200, 0
	s_or_b32 s12, s12, s14
	s_ashr_i32 s13, s12, 31
	v_lshl_add_u64 v[2:3], s[12:13], 2, v[22:23]
	s_mov_b64 s[12:13], 0
	v_mov_b32_e32 v4, v178
	v_mov_b32_e32 v5, v18
